# relaxed first-iteration vmcnt waits after GEMM epilogues (gemm1, ffn-up, down)
# speedup vs baseline: 1.0087x; 1.0007x over previous
; #define LAS __attribute__((address_space(3)))
; __device__ __forceinline__ unsigned xb_add(unsigned* p, unsigned v) { return __hip_atomic_fetch_add(p, v, __ATOMIC_RELAXED, __HIP_MEMORY_SCOPE_AGENT); }
; __device__ __forceinline__ unsigned xb_xcc_id() { return (unsigned)__builtin_amdgcn_s_getreg((3 << 11) | 20) & 0xFu; }
; __device__ __forceinline__ XcdBarrier xcd_barrier_post(unsigned* bar, volatile LAS unsigned* st) {
;     XcdBarrier b; b.bar = bar; b.x = xb_xcc_id(); b.st = st;
;     if (threadIdx.x == 0) (void)xb_add(&bar[XB_XCNT(b.x)], 1u);
;     return b;
; __global__ void __launch_bounds__(NTHR, 2) fwd_kernel(Params P) {
;     extern __shared__ __attribute__((aligned(16))) unsigned char smem[];
;     LAS unsigned char* lds = (LAS unsigned char*)smem;
;     cg::grid_group grid = cg::this_grid();
;     if (threadIdx.x < 4) ((LAS unsigned*)(lds + LDS_BYTES - 32))[threadIdx.x] = 0u;
;     __syncthreads();
;     const XcdBarrier xb = xcd_barrier_post((unsigned*)(P.ws + WS_BAR), (volatile LAS unsigned*)(lds + LDS_BYTES - 32));
_Z10fwd_kernel6Params:
	s_load_dwordx8 s[4:11], s[0:1], 0x80
	s_mov_b32 s100, 0
	s_load_dwordx4 s[72:75], s[0:1], 0xa0
	s_load_dwordx2 s[88:89], s[0:1], 0xb0
	s_mov_b32 s81, s2
	v_cmp_gt_u32_e32 vcc, 4, v0
	s_waitcnt lgkmcnt(0)
	v_writelane_b32 v251, s4, 0
	s_nop 1
	v_writelane_b32 v251, s5, 1
	v_writelane_b32 v251, s6, 2
	v_writelane_b32 v251, s7, 3
	v_writelane_b32 v251, s8, 4
	v_writelane_b32 v251, s9, 5
	v_writelane_b32 v251, s10, 6
	v_writelane_b32 v251, s11, 7
	s_and_saveexec_b64 s[4:5], vcc
	v_lshl_add_u32 v1, v0, 2, 0
	v_add_u32_e32 v1, 0x23fe0, v1
	v_mov_b32_e32 v2, 0
	ds_write_b32 v1, v2
	s_or_b64 exec, exec, s[4:5]
	s_load_dwordx2 s[94:95], s[0:1], 0xb8
	s_load_dword s2, s[0:1], 0xc0
	s_waitcnt lgkmcnt(0)
	s_barrier
	s_add_u32 s20, s74, 0x1000
	s_getreg_b32 s3, hwreg(HW_REG_XCC_ID, 0, 4)
	s_addc_u32 s21, s75, 0
	s_and_b32 s8, s3, 15
	v_cmp_eq_u32_e64 s[6:7], 0, v0
	s_mov_b64 s[4:5], exec
	s_nop 0
	v_writelane_b32 v251, s6, 8
	s_nop 1
	v_writelane_b32 v251, s7, 9
	s_and_b64 s[6:7], s[4:5], s[6:7]
	s_mov_b64 exec, s[6:7]
	s_cbranch_execz .LBB0_5
	s_mov_b64 s[6:7], exec
	v_mbcnt_lo_u32_b32 v1, s6, 0
	v_mbcnt_hi_u32_b32 v1, s7, v1
	v_cmp_eq_u32_e32 vcc, 0, v1
	s_and_b64 s[10:11], exec, vcc
	s_mov_b64 exec, s[10:11]
	s_cbranch_execz .LBB0_5
	s_lshl_b32 s3, s8, 8
	s_bcnt1_i32_b64 s6, s[6:7]
	v_mov_b32_e32 v1, s3
	v_mov_b32_e32 v2, s6
	global_atomic_add v1, v2, s[20:21] offset:1024

; template <class Epi>
; __device__ __forceinline__ void gemm_phase(LAS unsigned char* lds, const Gemm g, const Order& S, const Epi& E) {
;     ...
;     for (;;) {
;         const bool has_next = S.next(ui + 1, nxt);
;         const char* nA = has_next ? (const char*)(g.A + (size_t)nxt.g * g.gA) + (size_t)nxt.pm * tstepA : cA; const char* nB = has_next ? (const char*)(g.Bt + (size_t)nxt.g * g.gB) + (size_t)nxt.pn * tstepB : cB;
.LBB0_26:
	s_andn2_b64 vcc, exec, s[36:37]
	s_mov_b32 s14, s11
	s_mov_b32 s13, s12
	s_mov_b64 s[44:45], s[40:41]
	s_mov_b64 s[42:43], s[0:1]
	s_cbranch_vccz .LBB0_46
	s_mov_b32 s100, 1

; #define PG8_STAGE(bufoff, gbase, voff) do { _Pragma("unroll") for (int _i = 0; _i < 2; ++_i) \
;         __builtin_amdgcn_global_load_lds((const unsigned*)((const char*)(gbase) + (voff)[_i]), (LAS unsigned*)(lds + (bufoff) + ldsw + _i * 8192), 16, 0, 0); } while (0)
; #define PG8_LDA(dst, b, h) do { _Pragma("unroll") for (int m = 0; m < 4; ++m) _Pragma("unroll") for (int k = 0; k < 2; ++k) dst[m][k] = *(const LAS bf16x8*)(lds + PG8_SA(b, h) + aoff + m * 2048 + k * 1024); } while (0)
; #define PG8_LDB(dst, b, h) do { _Pragma("unroll") for (int n = 0; n < 2; ++n) _Pragma("unroll") for (int k = 0; k < 2; ++k) dst[n][k] = *(const LAS bf16x8*)(lds + PG8_SB(b, h) + boff + n * 2048 + k * 1024); } while (0)
; #define PG8_MMA(ai, bj, At, Bt) do { __builtin_amdgcn_s_setprio(1); _Pragma("unroll") for (int m = 0; m < 4; ++m) _Pragma("unroll") for (int n = 0; n < 2; ++n) _Pragma("unroll") for (int k = 0; k < 2; ++k) \
;         acc[ai][bj][m][n] = __builtin_amdgcn_mfma_f32_16x16x32_bf16(Bt[n][k], At[m][k], acc[ai][bj][m][n], 0, 0, 0); __builtin_amdgcn_s_setprio(0); } while (0)
; #define PG8_WAIT_V(n) asm volatile("s_waitcnt vmcnt(" #n ")" ::: "memory")
; #define PG8_WAIT_L(n) asm volatile("s_waitcnt lgkmcnt(" #n ")" ::: "memory")
; #define PG8_BAR __builtin_amdgcn_s_barrier()
; #define PG8_SCHED __builtin_amdgcn_sched_barrier(0)
; template <class Epi>
; __device__ __forceinline__ void gemm_phase(LAS unsigned char* lds, const Gemm g, const Order& S, const Epi& E) {
;     ...
;         for (int t = 0; t < nt; t += 2) {
;             const bool last = (t == nt - 2);
;             const char* a1 = cA + (size_t)(t + 1) * kstep;
;             const char* a2 = last ? nA : cA + (size_t)(t + 2) * kstep; const char* b2 = last ? nB : cB + (size_t)(t + 2) * kstep;
;             const char* a3 = a2 + kstep; const char* b3 = b2 + kstep;
;             PG8_LDB(B0, 0, 0); PG8_LDB(B1, 0, 1); PG8_SCHED; PG8_LDA(At, 0, 0); PG8_STAGE(PG8_SA(1, 1), a1 + hstepA, voffA);
;             PG8_WAIT_V(8); PG8_WAIT_L(0); PG8_BAR; PG8_MMA(0, 0, At, B0); PG8_MMA(0, 1, At, B1); PG8_BAR; PG8_SCHED;
;             PG8_LDA(At, 0, 1); PG8_STAGE(PG8_SB(0, 0), b2, voffB); PG8_STAGE(PG8_SB(0, 1), b2 + hstepB, voffB); PG8_STAGE(PG8_SA(0, 0), a2, voffA);
;             PG8_WAIT_V(8); PG8_WAIT_L(0); PG8_BAR; PG8_MMA(1, 0, At, B0); PG8_MMA(1, 1, At, B1); PG8_BAR; PG8_SCHED;
.LBB0_38:
	s_add_u32 s44, s42, 0x100
	s_addc_u32 s45, s43, 0
	s_add_i32 s18, 0, 0x10000
	s_cmp_eq_u32 s17, 40
	s_cselect_b32 s51, s1, s45
	s_cselect_b32 s50, s0, s44
	v_add_u32_e32 v140, s18, v143
	s_cselect_b32 s47, s41, s16
	s_cselect_b32 s46, s40, s15
	s_add_i32 s20, 0, 0x14000
	ds_read_b128 v[146:149], v140
	ds_read_b128 v[150:153], v140 offset:1024
	ds_read_b128 v[154:157], v140 offset:2048
	ds_read_b128 v[158:161], v140 offset:3072
	v_add_u32_e32 v140, s20, v143
	ds_read_b128 v[162:165], v140
	ds_read_b128 v[166:169], v140 offset:1024
	ds_read_b128 v[170:173], v140 offset:2048
	ds_read_b128 v[174:177], v140 offset:3072
	v_lshl_add_u64 v[140:141], s[42:43], 0, v[136:137]
	s_add_i32 m0, s4, 0xc000
	ds_read_b128 v[178:181], v145
	ds_read_b128 v[182:185], v145 offset:1024
	ds_read_b128 v[186:189], v145 offset:2048
	ds_read_b128 v[190:193], v145 offset:3072
	ds_read_b128 v[204:207], v145 offset:4096
	ds_read_b128 v[208:211], v145 offset:5120
	ds_read_b128 v[212:215], v145 offset:6144
	ds_read_b128 v[216:219], v145 offset:7168
	global_load_lds_dwordx4 v[140:141], off
	v_lshl_add_u64 v[140:141], s[42:43], 0, v[138:139]
	s_add_i32 m0, s4, 0xe000
	s_nop 0
	global_load_lds_dwordx4 v[140:141], off
	s_cmp_lg_u32 s100, 0
	s_cbranch_scc1 .Lxr1_LBB038
	s_waitcnt vmcnt(8)
	s_branch .Lxb1_LBB038
.Lxr1_LBB038:
	s_waitcnt vmcnt(24)
.Lxb1_LBB038:
	s_waitcnt lgkmcnt(0)
	s_barrier
	s_setprio 1
	s_waitcnt lgkmcnt(0)
	v_mfma_f32_16x16x32_bf16 v[126:129], v[146:149], v[178:181], v[126:129]
	v_mfma_f32_16x16x32_bf16 v[122:125], v[154:157], v[178:181], v[122:125]
	v_mfma_f32_16x16x32_bf16 v[114:117], v[146:149], v[186:189], v[114:117]
	v_mfma_f32_16x16x32_bf16 v[106:109], v[154:157], v[186:189], v[106:109]
	v_mfma_f32_16x16x32_bf16 v[98:101], v[146:149], v[204:207], v[98:101]
	v_mfma_f32_16x16x32_bf16 v[90:93], v[154:157], v[204:207], v[90:93]
	v_mfma_f32_16x16x32_bf16 v[82:85], v[146:149], v[212:215], v[82:85]
	v_mfma_f32_16x16x32_bf16 v[74:77], v[154:157], v[212:215], v[74:77]
	v_mfma_f32_16x16x32_bf16 v[126:129], v[150:153], v[182:185], v[126:129]
	v_mfma_f32_16x16x32_bf16 v[122:125], v[158:161], v[182:185], v[122:125]
	v_mfma_f32_16x16x32_bf16 v[114:117], v[150:153], v[190:193], v[114:117]
	v_mfma_f32_16x16x32_bf16 v[106:109], v[158:161], v[190:193], v[106:109]
	v_mfma_f32_16x16x32_bf16 v[98:101], v[150:153], v[208:211], v[98:101]
	v_mfma_f32_16x16x32_bf16 v[90:93], v[158:161], v[208:211], v[90:93]
	v_mfma_f32_16x16x32_bf16 v[82:85], v[150:153], v[216:219], v[82:85]
	v_mfma_f32_16x16x32_bf16 v[74:77], v[158:161], v[216:219], v[74:77]
	s_setprio 0
	s_setprio 1
	v_mfma_f32_16x16x32_bf16 v[118:121], v[162:165], v[178:181], v[118:121]
	v_mfma_f32_16x16x32_bf16 v[110:113], v[170:173], v[178:181], v[110:113]
	v_mfma_f32_16x16x32_bf16 v[102:105], v[162:165], v[186:189], v[102:105]
	v_mfma_f32_16x16x32_bf16 v[94:97], v[170:173], v[186:189], v[94:97]
	v_mfma_f32_16x16x32_bf16 v[86:89], v[162:165], v[204:207], v[86:89]
	v_mfma_f32_16x16x32_bf16 v[78:81], v[170:173], v[204:207], v[78:81]
	v_mfma_f32_16x16x32_bf16 v[70:73], v[162:165], v[212:215], v[70:73]
	v_mfma_f32_16x16x32_bf16 v[66:69], v[170:173], v[212:215], v[66:69]
	v_mfma_f32_16x16x32_bf16 v[118:121], v[166:169], v[182:185], v[118:121]
	v_mfma_f32_16x16x32_bf16 v[110:113], v[174:177], v[182:185], v[110:113]
	v_mfma_f32_16x16x32_bf16 v[102:105], v[166:169], v[190:193], v[102:105]
	v_mfma_f32_16x16x32_bf16 v[94:97], v[174:177], v[190:193], v[94:97]
	v_mfma_f32_16x16x32_bf16 v[86:89], v[166:169], v[208:211], v[86:89]
	v_mfma_f32_16x16x32_bf16 v[78:81], v[174:177], v[208:211], v[78:81]
	v_mfma_f32_16x16x32_bf16 v[70:73], v[166:169], v[216:219], v[70:73]
	v_mfma_f32_16x16x32_bf16 v[66:69], v[174:177], v[216:219], v[66:69]
	s_setprio 0
	s_barrier
	s_add_i32 s18, s18, s2
	v_lshl_add_u64 v[140:141], s[46:47], 0, v[194:195]
	s_mov_b32 m0, s18
	ds_read_b128 v[178:181], v145 offset:16384
	ds_read_b128 v[182:185], v145 offset:17408
	ds_read_b128 v[186:189], v145 offset:18432
	ds_read_b128 v[190:193], v145 offset:19456
	ds_read_b128 v[204:207], v145 offset:20480
	ds_read_b128 v[208:211], v145 offset:21504
	ds_read_b128 v[212:215], v145 offset:22528
	ds_read_b128 v[216:219], v145 offset:23552
	global_load_lds_dwordx4 v[140:141], off
	s_add_i32 m0, s18, 0x2000
	s_add_u32 s18, s46, 0xb0000
	v_lshl_add_u64 v[200:201], s[46:47], 0, v[130:131]
	s_addc_u32 s19, s47, 0
	s_add_i32 s20, s20, s2
	global_load_lds_dwordx4 v[200:201], off
	v_lshl_add_u64 v[220:221], s[18:19], 0, v[194:195]
	s_mov_b32 m0, s20
	v_lshl_add_u64 v[222:223], s[50:51], 0, v[132:133]
	global_load_lds_dwordx4 v[220:221], off
	v_lshl_add_u64 v[220:221], s[18:19], 0, v[130:131]
	s_add_i32 m0, s20, 0x2000
	s_nop 0
	global_load_lds_dwordx4 v[220:221], off
	v_lshl_add_u64 v[220:221], s[50:51], 0, v[134:135]
	s_mov_b32 m0, s4
	s_nop 0
	global_load_lds_dwordx4 v[220:221], off
	s_mov_b32 m0, s5
	s_nop 0
	global_load_lds_dwordx4 v[222:223], off
	s_cmp_lg_u32 s100, 0
	s_cbranch_scc1 .Lxr2_LBB038
	s_waitcnt vmcnt(8)
	s_branch .Lxb2_LBB038
.Lxr2_LBB038:
	s_waitcnt vmcnt(24)
	s_mov_b32 s100, 0
; #define PG8_STAGE(bufoff, gbase, voff) do { _Pragma("unroll") for (int _i = 0; _i < 2; ++_i) \
;         __builtin_amdgcn_global_load_lds((const unsigned*)((const char*)(gbase) + (voff)[_i]), (LAS unsigned*)(lds + (bufoff) + ldsw + _i * 8192), 16, 0, 0); } while (0)
; #define PG8_LDA(dst, b, h) do { _Pragma("unroll") for (int m = 0; m < 4; ++m) _Pragma("unroll") for (int k = 0; k < 2; ++k) dst[m][k] = *(const LAS bf16x8*)(lds + PG8_SA(b, h) + aoff + m * 2048 + k * 1024); } while (0)
; #define PG8_LDB(dst, b, h) do { _Pragma("unroll") for (int n = 0; n < 2; ++n) _Pragma("unroll") for (int k = 0; k < 2; ++k) dst[n][k] = *(const LAS bf16x8*)(lds + PG8_SB(b, h) + boff + n * 2048 + k * 1024); } while (0)
; #define PG8_MMA(ai, bj, At, Bt) do { __builtin_amdgcn_s_setprio(1); _Pragma("unroll") for (int m = 0; m < 4; ++m) _Pragma("unroll") for (int n = 0; n < 2; ++n) _Pragma("unroll") for (int k = 0; k < 2; ++k) \
;         acc[ai][bj][m][n] = __builtin_amdgcn_mfma_f32_16x16x32_bf16(Bt[n][k], At[m][k], acc[ai][bj][m][n], 0, 0, 0); __builtin_amdgcn_s_setprio(0); } while (0)
; #define PG8_WAIT_V(n) asm volatile("s_waitcnt vmcnt(" #n ")" ::: "memory")
; #define PG8_WAIT_L(n) asm volatile("s_waitcnt lgkmcnt(" #n ")" ::: "memory")
; #define PG8_BAR __builtin_amdgcn_s_barrier()
; #define PG8_SCHED __builtin_amdgcn_sched_barrier(0)
; template <class Epi>
; __device__ __forceinline__ void gemm_phase(LAS unsigned char* lds, const Gemm g, const Order& S, const Epi& E) {
;     ...
;             PG8_WAIT_V(8); PG8_WAIT_L(0); PG8_BAR; PG8_MMA(1, 0, At, B0); PG8_MMA(1, 1, At, B1); PG8_BAR; PG8_SCHED;
;             PG8_LDB(B0, 1, 0); PG8_LDB(B1, 1, 1); PG8_SCHED; PG8_LDA(At, 1, 0); PG8_STAGE(PG8_SA(0, 1), a2 + hstepA, voffA);
;             PG8_WAIT_V(8); PG8_WAIT_L(0); PG8_BAR; PG8_MMA(0, 0, At, B0); PG8_MMA(0, 1, At, B1); PG8_BAR; PG8_SCHED;
;             PG8_LDA(At, 1, 1); PG8_STAGE(PG8_SB(1, 0), b3, voffB); PG8_STAGE(PG8_SB(1, 1), b3 + hstepB, voffB); PG8_STAGE(PG8_SA(1, 0), a3, voffA);
;             PG8_WAIT_V(8); PG8_WAIT_L(0); PG8_BAR; PG8_MMA(1, 0, At, B0); PG8_MMA(1, 1, At, B1); PG8_BAR; PG8_SCHED;
.Lxb2_LBB038:
	s_waitcnt lgkmcnt(0)
	s_barrier
	s_setprio 1
	s_waitcnt lgkmcnt(0)
	v_mfma_f32_16x16x32_bf16 v[62:65], v[146:149], v[178:181], v[62:65]
	v_mfma_f32_16x16x32_bf16 v[58:61], v[154:157], v[178:181], v[58:61]
	v_mfma_f32_16x16x32_bf16 v[50:53], v[146:149], v[186:189], v[50:53]
	v_mfma_f32_16x16x32_bf16 v[42:45], v[154:157], v[186:189], v[42:45]
	v_mfma_f32_16x16x32_bf16 v[34:37], v[146:149], v[204:207], v[34:37]
	v_mfma_f32_16x16x32_bf16 v[26:29], v[154:157], v[204:207], v[26:29]
	v_mfma_f32_16x16x32_bf16 v[18:21], v[146:149], v[212:215], v[18:21]
	v_mfma_f32_16x16x32_bf16 v[10:13], v[154:157], v[212:215], v[10:13]
	v_mfma_f32_16x16x32_bf16 v[62:65], v[150:153], v[182:185], v[62:65]
	v_mfma_f32_16x16x32_bf16 v[58:61], v[158:161], v[182:185], v[58:61]
	v_mfma_f32_16x16x32_bf16 v[50:53], v[150:153], v[190:193], v[50:53]
	v_mfma_f32_16x16x32_bf16 v[42:45], v[158:161], v[190:193], v[42:45]
	v_mfma_f32_16x16x32_bf16 v[34:37], v[150:153], v[208:211], v[34:37]
	v_mfma_f32_16x16x32_bf16 v[26:29], v[158:161], v[208:211], v[26:29]
	v_mfma_f32_16x16x32_bf16 v[18:21], v[150:153], v[216:219], v[18:21]
	v_mfma_f32_16x16x32_bf16 v[10:13], v[158:161], v[216:219], v[10:13]
	s_setprio 0
	s_setprio 1
	v_mfma_f32_16x16x32_bf16 v[54:57], v[162:165], v[178:181], v[54:57]
	v_mfma_f32_16x16x32_bf16 v[46:49], v[170:173], v[178:181], v[46:49]
	v_mfma_f32_16x16x32_bf16 v[38:41], v[162:165], v[186:189], v[38:41]
	v_mfma_f32_16x16x32_bf16 v[30:33], v[170:173], v[186:189], v[30:33]
	v_mfma_f32_16x16x32_bf16 v[22:25], v[162:165], v[204:207], v[22:25]
	v_mfma_f32_16x16x32_bf16 v[14:17], v[170:173], v[204:207], v[14:17]
	v_mfma_f32_16x16x32_bf16 v[6:9], v[162:165], v[212:215], v[6:9]
	v_mfma_f32_16x16x32_bf16 v[2:5], v[170:173], v[212:215], v[2:5]
	v_mfma_f32_16x16x32_bf16 v[54:57], v[166:169], v[182:185], v[54:57]
	v_mfma_f32_16x16x32_bf16 v[46:49], v[174:177], v[182:185], v[46:49]
	v_mfma_f32_16x16x32_bf16 v[38:41], v[166:169], v[190:193], v[38:41]
	v_mfma_f32_16x16x32_bf16 v[30:33], v[174:177], v[190:193], v[30:33]
	v_mfma_f32_16x16x32_bf16 v[22:25], v[166:169], v[208:211], v[22:25]
	v_mfma_f32_16x16x32_bf16 v[14:17], v[174:177], v[208:211], v[14:17]
	v_mfma_f32_16x16x32_bf16 v[6:9], v[166:169], v[216:219], v[6:9]
	v_mfma_f32_16x16x32_bf16 v[2:5], v[174:177], v[216:219], v[2:5]
	s_setprio 0
	s_barrier
	s_add_i32 s20, 0, 0x18000
	s_add_i32 s42, 0, 0x1c000
	v_add_u32_e32 v158, s20, v143
	v_add_u32_e32 v174, s42, v143
	ds_read_b128 v[146:149], v158
	ds_read_b128 v[150:153], v158 offset:1024
	ds_read_b128 v[154:157], v158 offset:2048
	ds_read_b128 v[158:161], v158 offset:3072
	ds_read_b128 v[162:165], v174
	ds_read_b128 v[166:169], v174 offset:1024
	ds_read_b128 v[170:173], v174 offset:2048
	ds_read_b128 v[174:177], v174 offset:3072
	s_add_u32 s18, s50, 0xb0000
	s_addc_u32 s19, s51, 0
	s_mov_b32 m0, s6
	v_lshl_add_u64 v[224:225], s[18:19], 0, v[134:135]
	ds_read_b128 v[178:181], v145 offset:32768
	ds_read_b128 v[182:185], v145 offset:33792
	ds_read_b128 v[186:189], v145 offset:34816
	ds_read_b128 v[190:193], v145 offset:35840
	ds_read_b128 v[204:207], v145 offset:36864
	ds_read_b128 v[208:211], v145 offset:37888
	ds_read_b128 v[212:215], v145 offset:38912
	ds_read_b128 v[216:219], v145 offset:39936
	global_load_lds_dwordx4 v[224:225], off
	v_lshl_add_u64 v[224:225], s[18:19], 0, v[132:133]
	s_mov_b32 m0, s7
	s_nop 0
	global_load_lds_dwordx4 v[224:225], off
	s_waitcnt vmcnt(8)
	s_waitcnt lgkmcnt(0)
	s_barrier
	s_setprio 1
	s_waitcnt lgkmcnt(0)
	v_mfma_f32_16x16x32_bf16 v[126:129], v[146:149], v[178:181], v[126:129]
	v_mfma_f32_16x16x32_bf16 v[122:125], v[154:157], v[178:181], v[122:125]
	v_mfma_f32_16x16x32_bf16 v[114:117], v[146:149], v[186:189], v[114:117]
	v_mfma_f32_16x16x32_bf16 v[106:109], v[154:157], v[186:189], v[106:109]
	v_mfma_f32_16x16x32_bf16 v[98:101], v[146:149], v[204:207], v[98:101]
	v_mfma_f32_16x16x32_bf16 v[90:93], v[154:157], v[204:207], v[90:93]
	v_mfma_f32_16x16x32_bf16 v[82:85], v[146:149], v[212:215], v[82:85]
	v_mfma_f32_16x16x32_bf16 v[74:77], v[154:157], v[212:215], v[74:77]
	v_mfma_f32_16x16x32_bf16 v[126:129], v[150:153], v[182:185], v[126:129]
	v_mfma_f32_16x16x32_bf16 v[122:125], v[158:161], v[182:185], v[122:125]
	v_mfma_f32_16x16x32_bf16 v[114:117], v[150:153], v[190:193], v[114:117]
	v_mfma_f32_16x16x32_bf16 v[106:109], v[158:161], v[190:193], v[106:109]
	v_mfma_f32_16x16x32_bf16 v[98:101], v[150:153], v[208:211], v[98:101]
	v_mfma_f32_16x16x32_bf16 v[90:93], v[158:161], v[208:211], v[90:93]
	v_mfma_f32_16x16x32_bf16 v[82:85], v[150:153], v[216:219], v[82:85]
	v_mfma_f32_16x16x32_bf16 v[74:77], v[158:161], v[216:219], v[74:77]
	s_setprio 0
	s_setprio 1
	v_mfma_f32_16x16x32_bf16 v[118:121], v[162:165], v[178:181], v[118:121]
	v_mfma_f32_16x16x32_bf16 v[110:113], v[170:173], v[178:181], v[110:113]
	v_mfma_f32_16x16x32_bf16 v[102:105], v[162:165], v[186:189], v[102:105]
	v_mfma_f32_16x16x32_bf16 v[94:97], v[170:173], v[186:189], v[94:97]
	v_mfma_f32_16x16x32_bf16 v[86:89], v[162:165], v[204:207], v[86:89]
	v_mfma_f32_16x16x32_bf16 v[78:81], v[170:173], v[204:207], v[78:81]
	v_mfma_f32_16x16x32_bf16 v[70:73], v[162:165], v[212:215], v[70:73]
	v_mfma_f32_16x16x32_bf16 v[66:69], v[170:173], v[212:215], v[66:69]
	v_mfma_f32_16x16x32_bf16 v[118:121], v[166:169], v[182:185], v[118:121]
	v_mfma_f32_16x16x32_bf16 v[110:113], v[174:177], v[182:185], v[110:113]
	v_mfma_f32_16x16x32_bf16 v[102:105], v[166:169], v[190:193], v[102:105]
	v_mfma_f32_16x16x32_bf16 v[94:97], v[174:177], v[190:193], v[94:97]
	v_mfma_f32_16x16x32_bf16 v[86:89], v[166:169], v[208:211], v[86:89]
	v_mfma_f32_16x16x32_bf16 v[78:81], v[174:177], v[208:211], v[78:81]
	v_mfma_f32_16x16x32_bf16 v[70:73], v[166:169], v[216:219], v[70:73]
	v_mfma_f32_16x16x32_bf16 v[66:69], v[174:177], v[216:219], v[66:69]
	s_setprio 0
	s_barrier
; #define PG8_STAGE(bufoff, gbase, voff) do { _Pragma("unroll") for (int _i = 0; _i < 2; ++_i) \
;         __builtin_amdgcn_global_load_lds((const unsigned*)((const char*)(gbase) + (voff)[_i]), (LAS unsigned*)(lds + (bufoff) + ldsw + _i * 8192), 16, 0, 0); } while (0)
; #define PG8_LDA(dst, b, h) do { _Pragma("unroll") for (int m = 0; m < 4; ++m) _Pragma("unroll") for (int k = 0; k < 2; ++k) dst[m][k] = *(const LAS bf16x8*)(lds + PG8_SA(b, h) + aoff + m * 2048 + k * 1024); } while (0)
; #define PG8_MMA(ai, bj, At, Bt) do { __builtin_amdgcn_s_setprio(1); _Pragma("unroll") for (int m = 0; m < 4; ++m) _Pragma("unroll") for (int n = 0; n < 2; ++n) _Pragma("unroll") for (int k = 0; k < 2; ++k) \
;         acc[ai][bj][m][n] = __builtin_amdgcn_mfma_f32_16x16x32_bf16(Bt[n][k], At[m][k], acc[ai][bj][m][n], 0, 0, 0); __builtin_amdgcn_s_setprio(0); } while (0)
; #define PG8_WAIT_V(n) asm volatile("s_waitcnt vmcnt(" #n ")" ::: "memory")
; #define PG8_WAIT_L(n) asm volatile("s_waitcnt lgkmcnt(" #n ")" ::: "memory")
; #define PG8_BAR __builtin_amdgcn_s_barrier()
; #define PG8_SCHED __builtin_amdgcn_sched_barrier(0)
; template <class Epi>
; __device__ __forceinline__ void gemm_phase(LAS unsigned char* lds, const Gemm g, const Order& S, const Epi& E) {
;     ...
;             PG8_LDA(At, 1, 1); PG8_STAGE(PG8_SB(1, 0), b3, voffB); PG8_STAGE(PG8_SB(1, 1), b3 + hstepB, voffB); PG8_STAGE(PG8_SA(1, 0), a3, voffA);
;             PG8_WAIT_V(8); PG8_WAIT_L(0); PG8_BAR; PG8_MMA(1, 0, At, B0); PG8_MMA(1, 1, At, B1); PG8_BAR; PG8_SCHED;
;         }
;         if (wr == 0) PG8_BAR;
	s_add_i32 s18, s20, s2
	v_lshl_add_u64 v[140:141], v[140:141], 0, s[86:87]
	s_mov_b32 m0, s18
	ds_read_b128 v[178:181], v145 offset:49152
	ds_read_b128 v[182:185], v145 offset:50176
	ds_read_b128 v[186:189], v145 offset:51200
	ds_read_b128 v[190:193], v145 offset:52224
	ds_read_b128 v[204:207], v145 offset:53248
	ds_read_b128 v[208:211], v145 offset:54272
	ds_read_b128 v[212:215], v145 offset:55296
	ds_read_b128 v[216:219], v145 offset:56320
	global_load_lds_dwordx4 v[140:141], off
	s_add_i32 m0, s18, 0x2000
	s_add_u32 s18, s46, 0xb0080
	v_lshl_add_u64 v[140:141], v[200:201], 0, s[86:87]
	s_addc_u32 s19, s47, 0
	s_add_i32 s20, s42, s2
	global_load_lds_dwordx4 v[140:141], off
	v_lshl_add_u64 v[140:141], s[18:19], 0, v[194:195]
	s_mov_b32 m0, s20
	s_nop 0
	global_load_lds_dwordx4 v[140:141], off
	v_lshl_add_u64 v[140:141], s[18:19], 0, v[130:131]
	s_add_i32 m0, s20, 0x2000
	s_nop 0
	global_load_lds_dwordx4 v[140:141], off
	v_lshl_add_u64 v[140:141], v[220:221], 0, s[86:87]
	s_mov_b32 m0, s8
	s_nop 0
	global_load_lds_dwordx4 v[140:141], off
	v_lshl_add_u64 v[140:141], v[222:223], 0, s[86:87]
	s_mov_b32 m0, s9
	s_nop 0
	global_load_lds_dwordx4 v[140:141], off
	s_waitcnt vmcnt(8)
	s_waitcnt lgkmcnt(0)
	s_barrier
	s_setprio 1
	s_waitcnt lgkmcnt(0)
	v_mfma_f32_16x16x32_bf16 v[62:65], v[146:149], v[178:181], v[62:65]
	v_mfma_f32_16x16x32_bf16 v[58:61], v[154:157], v[178:181], v[58:61]
	v_mfma_f32_16x16x32_bf16 v[50:53], v[146:149], v[186:189], v[50:53]
	v_mfma_f32_16x16x32_bf16 v[42:45], v[154:157], v[186:189], v[42:45]
	v_mfma_f32_16x16x32_bf16 v[34:37], v[146:149], v[204:207], v[34:37]
	v_mfma_f32_16x16x32_bf16 v[26:29], v[154:157], v[204:207], v[26:29]
	v_mfma_f32_16x16x32_bf16 v[18:21], v[146:149], v[212:215], v[18:21]
	v_mfma_f32_16x16x32_bf16 v[10:13], v[154:157], v[212:215], v[10:13]
	v_mfma_f32_16x16x32_bf16 v[62:65], v[150:153], v[182:185], v[62:65]
	v_mfma_f32_16x16x32_bf16 v[58:61], v[158:161], v[182:185], v[58:61]
	v_mfma_f32_16x16x32_bf16 v[50:53], v[150:153], v[190:193], v[50:53]
	v_mfma_f32_16x16x32_bf16 v[42:45], v[158:161], v[190:193], v[42:45]
	v_mfma_f32_16x16x32_bf16 v[34:37], v[150:153], v[208:211], v[34:37]
	v_mfma_f32_16x16x32_bf16 v[26:29], v[158:161], v[208:211], v[26:29]
	v_mfma_f32_16x16x32_bf16 v[18:21], v[150:153], v[216:219], v[18:21]
	v_mfma_f32_16x16x32_bf16 v[10:13], v[158:161], v[216:219], v[10:13]
	s_setprio 0
	s_setprio 1
	v_mfma_f32_16x16x32_bf16 v[54:57], v[162:165], v[178:181], v[54:57]
	v_mfma_f32_16x16x32_bf16 v[46:49], v[170:173], v[178:181], v[46:49]
	v_mfma_f32_16x16x32_bf16 v[38:41], v[162:165], v[186:189], v[38:41]
	v_mfma_f32_16x16x32_bf16 v[30:33], v[170:173], v[186:189], v[30:33]
	v_mfma_f32_16x16x32_bf16 v[22:25], v[162:165], v[204:207], v[22:25]
	v_mfma_f32_16x16x32_bf16 v[14:17], v[170:173], v[204:207], v[14:17]
	v_mfma_f32_16x16x32_bf16 v[6:9], v[162:165], v[212:215], v[6:9]
	v_mfma_f32_16x16x32_bf16 v[2:5], v[170:173], v[212:215], v[2:5]
	v_mfma_f32_16x16x32_bf16 v[54:57], v[166:169], v[182:185], v[54:57]
	v_mfma_f32_16x16x32_bf16 v[46:49], v[174:177], v[182:185], v[46:49]
	v_mfma_f32_16x16x32_bf16 v[38:41], v[166:169], v[190:193], v[38:41]
	v_mfma_f32_16x16x32_bf16 v[30:33], v[174:177], v[190:193], v[30:33]
	v_mfma_f32_16x16x32_bf16 v[22:25], v[166:169], v[208:211], v[22:25]
	v_mfma_f32_16x16x32_bf16 v[14:17], v[174:177], v[208:211], v[14:17]
	v_mfma_f32_16x16x32_bf16 v[6:9], v[166:169], v[216:219], v[6:9]
	v_mfma_f32_16x16x32_bf16 v[2:5], v[174:177], v[216:219], v[2:5]
	s_setprio 0
	s_barrier
	s_add_i32 s17, s17, 2
	s_add_u32 s15, s15, 0x100
	s_addc_u32 s16, s16, 0
	s_cmp_gt_u32 s17, 41
	s_mov_b64 s[42:43], s[44:45]
	s_cbranch_scc0 .LBB0_38
	s_and_b64 vcc, exec, s[38:39]
	s_cbranch_vccz .LBB0_41
	s_barrier

; template <class Epi>
; __device__ __forceinline__ void gemm_phase(LAS unsigned char* lds, const Gemm g, const Order& S, const Epi& E) {
;     ...
;     for (;;) {
;         const bool has_next = S.next(ui + 1, nxt);
;         const char* nA = has_next ? (const char*)(g.A + (size_t)nxt.g * g.gA) + (size_t)nxt.pm * tstepA : cA; const char* nB = has_next ? (const char*)(g.Bt + (size_t)nxt.g * g.gB) + (size_t)nxt.pn * tstepB : cB;
.LBB0_67:
	s_andn2_b64 vcc, exec, s[30:31]
	s_mov_b32 s7, s80
	s_mov_b32 s30, s82
	s_mov_b64 s[48:49], s[50:51]
	s_mov_b64 s[46:47], s[90:91]
	s_cbranch_vccz .LBB0_91
	s_mov_b32 s100, 1

; #define PG8_STAGE(bufoff, gbase, voff) do { _Pragma("unroll") for (int _i = 0; _i < 2; ++_i) \
;         __builtin_amdgcn_global_load_lds((const unsigned*)((const char*)(gbase) + (voff)[_i]), (LAS unsigned*)(lds + (bufoff) + ldsw + _i * 8192), 16, 0, 0); } while (0)
; #define PG8_LDA(dst, b, h) do { _Pragma("unroll") for (int m = 0; m < 4; ++m) _Pragma("unroll") for (int k = 0; k < 2; ++k) dst[m][k] = *(const LAS bf16x8*)(lds + PG8_SA(b, h) + aoff + m * 2048 + k * 1024); } while (0)
; #define PG8_LDB(dst, b, h) do { _Pragma("unroll") for (int n = 0; n < 2; ++n) _Pragma("unroll") for (int k = 0; k < 2; ++k) dst[n][k] = *(const LAS bf16x8*)(lds + PG8_SB(b, h) + boff + n * 2048 + k * 1024); } while (0)
; #define PG8_MMA(ai, bj, At, Bt) do { __builtin_amdgcn_s_setprio(1); _Pragma("unroll") for (int m = 0; m < 4; ++m) _Pragma("unroll") for (int n = 0; n < 2; ++n) _Pragma("unroll") for (int k = 0; k < 2; ++k) \
;         acc[ai][bj][m][n] = __builtin_amdgcn_mfma_f32_16x16x32_bf16(Bt[n][k], At[m][k], acc[ai][bj][m][n], 0, 0, 0); __builtin_amdgcn_s_setprio(0); } while (0)
; #define PG8_WAIT_V(n) asm volatile("s_waitcnt vmcnt(" #n ")" ::: "memory")
; #define PG8_WAIT_L(n) asm volatile("s_waitcnt lgkmcnt(" #n ")" ::: "memory")
; #define PG8_BAR __builtin_amdgcn_s_barrier()
; #define PG8_SCHED __builtin_amdgcn_sched_barrier(0)
; template <class Epi>
; __device__ __forceinline__ void gemm_phase(LAS unsigned char* lds, const Gemm g, const Order& S, const Epi& E) {
;     ...
;         for (int t = 0; t < nt; t += 2) {
;             const bool last = (t == nt - 2);
;             const char* a1 = cA + (size_t)(t + 1) * kstep;
;             const char* a2 = last ? nA : cA + (size_t)(t + 2) * kstep; const char* b2 = last ? nB : cB + (size_t)(t + 2) * kstep;
;             const char* a3 = a2 + kstep; const char* b3 = b2 + kstep;
;             PG8_LDB(B0, 0, 0); PG8_LDB(B1, 0, 1); PG8_SCHED; PG8_LDA(At, 0, 0); PG8_STAGE(PG8_SA(1, 1), a1 + hstepA, voffA);
;             PG8_WAIT_V(8); PG8_WAIT_L(0); PG8_BAR; PG8_MMA(0, 0, At, B0); PG8_MMA(0, 1, At, B1); PG8_BAR; PG8_SCHED;
;             PG8_LDA(At, 0, 1); PG8_STAGE(PG8_SB(0, 0), b2, voffB); PG8_STAGE(PG8_SB(0, 1), b2 + hstepB, voffB); PG8_STAGE(PG8_SA(0, 0), a2, voffA);
;             PG8_WAIT_V(8); PG8_WAIT_L(0); PG8_BAR; PG8_MMA(1, 0, At, B0); PG8_MMA(1, 1, At, B1); PG8_BAR; PG8_SCHED;
.LBB0_71:
	s_add_u32 s15, s46, 0xfffc0080
	s_addc_u32 s16, s47, -1
	s_add_i32 s17, 0, 0x10000
	s_cmp_eq_u32 s14, 12
	s_cselect_b32 s49, s8, s16
	s_cselect_b32 s48, s9, s15
	s_cselect_b32 vcc_hi, s10, s13
	s_cselect_b32 vcc_lo, s11, s12
	s_add_i32 s15, 0, 0x14000
	v_add_u32_e32 v78, s17, v205
	v_add_u32_e32 v102, s15, v205
	ds_read_b128 v[66:69], v78
	ds_read_b128 v[70:73], v78 offset:1024
	ds_read_b128 v[74:77], v78 offset:2048
	ds_read_b128 v[78:81], v78 offset:3072
	ds_read_b128 v[90:93], v102
	ds_read_b128 v[94:97], v102 offset:1024
	ds_read_b128 v[98:101], v102 offset:2048
	ds_read_b128 v[102:105], v102 offset:3072
	v_lshl_add_u64 v[192:193], s[46:47], 0, v[188:189]
	s_add_i32 m0, s20, 0xc000
	ds_read_b128 v[162:165], v208
	ds_read_b128 v[166:169], v208 offset:1024
	ds_read_b128 v[170:173], v208 offset:2048
	ds_read_b128 v[174:177], v208 offset:3072
	ds_read_b128 v[210:213], v208 offset:4096
	ds_read_b128 v[214:217], v208 offset:5120
	ds_read_b128 v[218:221], v208 offset:6144
	ds_read_b128 v[222:225], v208 offset:7168
	global_load_lds_dwordx4 v[192:193], off
	v_lshl_add_u64 v[192:193], s[46:47], 0, v[190:191]
	s_add_i32 m0, s20, 0xe000
	s_nop 0
	global_load_lds_dwordx4 v[192:193], off
	s_cmp_lg_u32 s100, 0
	s_cbranch_scc1 .Lxr1_LBB071
	s_waitcnt vmcnt(8)
	s_branch .Lxb1_LBB071
.Lxr1_LBB071:
	s_waitcnt vmcnt(15)
.Lxb1_LBB071:
	s_waitcnt lgkmcnt(0)
	s_barrier
	s_setprio 1
	s_waitcnt lgkmcnt(0)
	v_mfma_f32_16x16x32_bf16 v[150:153], v[66:69], v[162:165], v[150:153]
	v_mfma_f32_16x16x32_bf16 v[146:149], v[74:77], v[162:165], v[146:149]
	v_mfma_f32_16x16x32_bf16 v[134:137], v[66:69], v[170:173], v[134:137]
	v_mfma_f32_16x16x32_bf16 v[130:133], v[74:77], v[170:173], v[130:133]
	v_mfma_f32_16x16x32_bf16 v[118:121], v[66:69], v[210:213], v[118:121]
	v_mfma_f32_16x16x32_bf16 v[114:117], v[74:77], v[210:213], v[114:117]
	v_mfma_f32_16x16x32_bf16 v[110:113], v[66:69], v[218:221], v[110:113]
	v_mfma_f32_16x16x32_bf16 v[106:109], v[74:77], v[218:221], v[106:109]
	v_mfma_f32_16x16x32_bf16 v[150:153], v[70:73], v[166:169], v[150:153]
	v_mfma_f32_16x16x32_bf16 v[146:149], v[78:81], v[166:169], v[146:149]
	v_mfma_f32_16x16x32_bf16 v[134:137], v[70:73], v[174:177], v[134:137]
	v_mfma_f32_16x16x32_bf16 v[130:133], v[78:81], v[174:177], v[130:133]
	v_mfma_f32_16x16x32_bf16 v[118:121], v[70:73], v[214:217], v[118:121]
	v_mfma_f32_16x16x32_bf16 v[114:117], v[78:81], v[214:217], v[114:117]
	v_mfma_f32_16x16x32_bf16 v[110:113], v[70:73], v[222:225], v[110:113]
	v_mfma_f32_16x16x32_bf16 v[106:109], v[78:81], v[222:225], v[106:109]
	s_setprio 0
	s_setprio 1
	v_mfma_f32_16x16x32_bf16 v[154:157], v[90:93], v[162:165], v[154:157]
	v_mfma_f32_16x16x32_bf16 v[158:161], v[98:101], v[162:165], v[158:161]
	v_mfma_f32_16x16x32_bf16 v[142:145], v[90:93], v[170:173], v[142:145]
	v_mfma_f32_16x16x32_bf16 v[138:141], v[98:101], v[170:173], v[138:141]
	v_mfma_f32_16x16x32_bf16 v[126:129], v[90:93], v[210:213], v[126:129]
	v_mfma_f32_16x16x32_bf16 v[122:125], v[98:101], v[210:213], v[122:125]
	v_mfma_f32_16x16x32_bf16 v[86:89], v[90:93], v[218:221], v[86:89]
	v_mfma_f32_16x16x32_bf16 v[82:85], v[98:101], v[218:221], v[82:85]
	v_mfma_f32_16x16x32_bf16 v[154:157], v[94:97], v[166:169], v[154:157]
	v_mfma_f32_16x16x32_bf16 v[158:161], v[102:105], v[166:169], v[158:161]
	v_mfma_f32_16x16x32_bf16 v[142:145], v[94:97], v[174:177], v[142:145]
	v_mfma_f32_16x16x32_bf16 v[138:141], v[102:105], v[174:177], v[138:141]
	v_mfma_f32_16x16x32_bf16 v[126:129], v[94:97], v[214:217], v[126:129]
	v_mfma_f32_16x16x32_bf16 v[122:125], v[102:105], v[214:217], v[122:125]
	v_mfma_f32_16x16x32_bf16 v[86:89], v[94:97], v[222:225], v[86:89]
	v_mfma_f32_16x16x32_bf16 v[82:85], v[102:105], v[222:225], v[82:85]
	s_setprio 0
	s_barrier
	s_add_i32 s16, s17, s2
	v_lshl_add_u64 v[192:193], vcc, 0, v[194:195]
	s_mov_b32 m0, s16
	ds_read_b128 v[162:165], v208 offset:16384
	ds_read_b128 v[166:169], v208 offset:17408
	ds_read_b128 v[170:173], v208 offset:18432
	ds_read_b128 v[174:177], v208 offset:19456
	ds_read_b128 v[210:213], v208 offset:20480
	ds_read_b128 v[214:217], v208 offset:21504
	ds_read_b128 v[218:221], v208 offset:22528
	ds_read_b128 v[222:225], v208 offset:23552
	global_load_lds_dwordx4 v[192:193], off
	s_add_i32 m0, s16, 0x2000
	s_add_u32 s16, vcc_lo, 0x40000
	v_lshl_add_u64 v[200:201], vcc, 0, v[178:179]
	s_addc_u32 s17, vcc_hi, 0
	s_add_i32 s15, s15, s2
	global_load_lds_dwordx4 v[200:201], off
	v_lshl_add_u64 v[226:227], s[16:17], 0, v[194:195]
	s_mov_b32 m0, s15
	v_lshl_add_u64 v[228:229], s[48:49], 0, v[180:181]
	global_load_lds_dwordx4 v[226:227], off
	v_lshl_add_u64 v[226:227], s[16:17], 0, v[178:179]
	s_add_i32 m0, s15, 0x2000
	s_nop 0
	global_load_lds_dwordx4 v[226:227], off
	v_lshl_add_u64 v[226:227], s[48:49], 0, v[182:183]
	s_mov_b32 m0, s20
	s_nop 0
	global_load_lds_dwordx4 v[226:227], off
	s_mov_b32 m0, s88
	s_nop 0
	global_load_lds_dwordx4 v[228:229], off
	s_cmp_lg_u32 s100, 0
	s_cbranch_scc1 .Lxr2_LBB071
	s_waitcnt vmcnt(8)
	s_branch .Lxb2_LBB071
.Lxr2_LBB071:
	s_waitcnt vmcnt(15)
	s_mov_b32 s100, 0
; #define PG8_STAGE(bufoff, gbase, voff) do { _Pragma("unroll") for (int _i = 0; _i < 2; ++_i) \
;         __builtin_amdgcn_global_load_lds((const unsigned*)((const char*)(gbase) + (voff)[_i]), (LAS unsigned*)(lds + (bufoff) + ldsw + _i * 8192), 16, 0, 0); } while (0)
; #define PG8_LDA(dst, b, h) do { _Pragma("unroll") for (int m = 0; m < 4; ++m) _Pragma("unroll") for (int k = 0; k < 2; ++k) dst[m][k] = *(const LAS bf16x8*)(lds + PG8_SA(b, h) + aoff + m * 2048 + k * 1024); } while (0)
; #define PG8_LDB(dst, b, h) do { _Pragma("unroll") for (int n = 0; n < 2; ++n) _Pragma("unroll") for (int k = 0; k < 2; ++k) dst[n][k] = *(const LAS bf16x8*)(lds + PG8_SB(b, h) + boff + n * 2048 + k * 1024); } while (0)
; #define PG8_MMA(ai, bj, At, Bt) do { __builtin_amdgcn_s_setprio(1); _Pragma("unroll") for (int m = 0; m < 4; ++m) _Pragma("unroll") for (int n = 0; n < 2; ++n) _Pragma("unroll") for (int k = 0; k < 2; ++k) \
;         acc[ai][bj][m][n] = __builtin_amdgcn_mfma_f32_16x16x32_bf16(Bt[n][k], At[m][k], acc[ai][bj][m][n], 0, 0, 0); __builtin_amdgcn_s_setprio(0); } while (0)
; #define PG8_WAIT_V(n) asm volatile("s_waitcnt vmcnt(" #n ")" ::: "memory")
; #define PG8_WAIT_L(n) asm volatile("s_waitcnt lgkmcnt(" #n ")" ::: "memory")
; #define PG8_BAR __builtin_amdgcn_s_barrier()
; #define PG8_SCHED __builtin_amdgcn_sched_barrier(0)
; template <class Epi>
; __device__ __forceinline__ void gemm_phase(LAS unsigned char* lds, const Gemm g, const Order& S, const Epi& E) {
;     ...
;             PG8_WAIT_V(8); PG8_WAIT_L(0); PG8_BAR; PG8_MMA(1, 0, At, B0); PG8_MMA(1, 1, At, B1); PG8_BAR; PG8_SCHED;
;             PG8_LDB(B0, 1, 0); PG8_LDB(B1, 1, 1); PG8_SCHED; PG8_LDA(At, 1, 0); PG8_STAGE(PG8_SA(0, 1), a2 + hstepA, voffA);
;             PG8_WAIT_V(8); PG8_WAIT_L(0); PG8_BAR; PG8_MMA(0, 0, At, B0); PG8_MMA(0, 1, At, B1); PG8_BAR; PG8_SCHED;
;             PG8_LDA(At, 1, 1); PG8_STAGE(PG8_SB(1, 0), b3, voffB); PG8_STAGE(PG8_SB(1, 1), b3 + hstepB, voffB); PG8_STAGE(PG8_SA(1, 0), a3, voffA);
;             PG8_WAIT_V(8); PG8_WAIT_L(0); PG8_BAR; PG8_MMA(1, 0, At, B0); PG8_MMA(1, 1, At, B1); PG8_BAR; PG8_SCHED;
.Lxb2_LBB071:
	s_waitcnt lgkmcnt(0)
	s_barrier
	s_setprio 1
	s_waitcnt lgkmcnt(0)
	v_mfma_f32_16x16x32_bf16 v[54:57], v[66:69], v[162:165], v[54:57]
	v_mfma_f32_16x16x32_bf16 v[50:53], v[74:77], v[162:165], v[50:53]
	v_mfma_f32_16x16x32_bf16 v[38:41], v[66:69], v[170:173], v[38:41]
	v_mfma_f32_16x16x32_bf16 v[34:37], v[74:77], v[170:173], v[34:37]
	v_mfma_f32_16x16x32_bf16 v[22:25], v[66:69], v[210:213], v[22:25]
	v_mfma_f32_16x16x32_bf16 v[18:21], v[74:77], v[210:213], v[18:21]
	v_mfma_f32_16x16x32_bf16 v[14:17], v[66:69], v[218:221], v[14:17]
	v_mfma_f32_16x16x32_bf16 v[10:13], v[74:77], v[218:221], v[10:13]
	v_mfma_f32_16x16x32_bf16 v[54:57], v[70:73], v[166:169], v[54:57]
	v_mfma_f32_16x16x32_bf16 v[50:53], v[78:81], v[166:169], v[50:53]
	v_mfma_f32_16x16x32_bf16 v[38:41], v[70:73], v[174:177], v[38:41]
	v_mfma_f32_16x16x32_bf16 v[34:37], v[78:81], v[174:177], v[34:37]
	v_mfma_f32_16x16x32_bf16 v[22:25], v[70:73], v[214:217], v[22:25]
	v_mfma_f32_16x16x32_bf16 v[18:21], v[78:81], v[214:217], v[18:21]
	v_mfma_f32_16x16x32_bf16 v[14:17], v[70:73], v[222:225], v[14:17]
	v_mfma_f32_16x16x32_bf16 v[10:13], v[78:81], v[222:225], v[10:13]
	s_setprio 0
	s_setprio 1
	v_mfma_f32_16x16x32_bf16 v[58:61], v[90:93], v[162:165], v[58:61]
	v_mfma_f32_16x16x32_bf16 v[62:65], v[98:101], v[162:165], v[62:65]
	v_mfma_f32_16x16x32_bf16 v[46:49], v[90:93], v[170:173], v[46:49]
	v_mfma_f32_16x16x32_bf16 v[42:45], v[98:101], v[170:173], v[42:45]
	v_mfma_f32_16x16x32_bf16 v[30:33], v[90:93], v[210:213], v[30:33]
	v_mfma_f32_16x16x32_bf16 v[26:29], v[98:101], v[210:213], v[26:29]
	v_mfma_f32_16x16x32_bf16 v[6:9], v[90:93], v[218:221], v[6:9]
	v_mfma_f32_16x16x32_bf16 v[2:5], v[98:101], v[218:221], v[2:5]
	v_mfma_f32_16x16x32_bf16 v[58:61], v[94:97], v[166:169], v[58:61]
	v_mfma_f32_16x16x32_bf16 v[62:65], v[102:105], v[166:169], v[62:65]
	v_mfma_f32_16x16x32_bf16 v[46:49], v[94:97], v[174:177], v[46:49]
	v_mfma_f32_16x16x32_bf16 v[42:45], v[102:105], v[174:177], v[42:45]
	v_mfma_f32_16x16x32_bf16 v[30:33], v[94:97], v[214:217], v[30:33]
	v_mfma_f32_16x16x32_bf16 v[26:29], v[102:105], v[214:217], v[26:29]
	v_mfma_f32_16x16x32_bf16 v[6:9], v[94:97], v[222:225], v[6:9]
	v_mfma_f32_16x16x32_bf16 v[2:5], v[102:105], v[222:225], v[2:5]
	s_setprio 0
	s_barrier
	s_add_i32 s15, 0, 0x18000
	s_add_i32 s18, 0, 0x1c000
	v_add_u32_e32 v78, s15, v205
	v_add_u32_e32 v102, s18, v205
	ds_read_b128 v[66:69], v78
	ds_read_b128 v[70:73], v78 offset:1024
	ds_read_b128 v[74:77], v78 offset:2048
	ds_read_b128 v[78:81], v78 offset:3072
	ds_read_b128 v[90:93], v102
	ds_read_b128 v[94:97], v102 offset:1024
	ds_read_b128 v[98:101], v102 offset:2048
	ds_read_b128 v[102:105], v102 offset:3072
	s_add_u32 s16, s48, 0x40000
	s_addc_u32 s17, s49, 0
	s_mov_b32 m0, s89
	v_lshl_add_u64 v[236:237], s[16:17], 0, v[182:183]
	ds_read_b128 v[162:165], v208 offset:32768
	ds_read_b128 v[166:169], v208 offset:33792
	ds_read_b128 v[170:173], v208 offset:34816
	ds_read_b128 v[174:177], v208 offset:35840
	ds_read_b128 v[210:213], v208 offset:36864
	ds_read_b128 v[214:217], v208 offset:37888
	ds_read_b128 v[218:221], v208 offset:38912
	ds_read_b128 v[222:225], v208 offset:39936
	global_load_lds_dwordx4 v[236:237], off
	v_lshl_add_u64 v[236:237], s[16:17], 0, v[180:181]
	s_mov_b32 m0, s93
	s_nop 0
	global_load_lds_dwordx4 v[236:237], off
	s_waitcnt vmcnt(8)
	s_waitcnt lgkmcnt(0)
	s_barrier
	s_setprio 1
	s_waitcnt lgkmcnt(0)
	v_mfma_f32_16x16x32_bf16 v[150:153], v[66:69], v[162:165], v[150:153]
	v_mfma_f32_16x16x32_bf16 v[146:149], v[74:77], v[162:165], v[146:149]
	v_mfma_f32_16x16x32_bf16 v[134:137], v[66:69], v[170:173], v[134:137]
	v_mfma_f32_16x16x32_bf16 v[130:133], v[74:77], v[170:173], v[130:133]
	v_mfma_f32_16x16x32_bf16 v[118:121], v[66:69], v[210:213], v[118:121]
	v_mfma_f32_16x16x32_bf16 v[114:117], v[74:77], v[210:213], v[114:117]
	v_mfma_f32_16x16x32_bf16 v[110:113], v[66:69], v[218:221], v[110:113]
	v_mfma_f32_16x16x32_bf16 v[106:109], v[74:77], v[218:221], v[106:109]
	v_mfma_f32_16x16x32_bf16 v[150:153], v[70:73], v[166:169], v[150:153]
	v_mfma_f32_16x16x32_bf16 v[146:149], v[78:81], v[166:169], v[146:149]
	v_mfma_f32_16x16x32_bf16 v[134:137], v[70:73], v[174:177], v[134:137]
	v_mfma_f32_16x16x32_bf16 v[130:133], v[78:81], v[174:177], v[130:133]
	v_mfma_f32_16x16x32_bf16 v[118:121], v[70:73], v[214:217], v[118:121]
	v_mfma_f32_16x16x32_bf16 v[114:117], v[78:81], v[214:217], v[114:117]
	v_mfma_f32_16x16x32_bf16 v[110:113], v[70:73], v[222:225], v[110:113]
	v_mfma_f32_16x16x32_bf16 v[106:109], v[78:81], v[222:225], v[106:109]
	s_setprio 0
	s_setprio 1
	v_mfma_f32_16x16x32_bf16 v[154:157], v[90:93], v[162:165], v[154:157]
	v_mfma_f32_16x16x32_bf16 v[158:161], v[98:101], v[162:165], v[158:161]
	v_mfma_f32_16x16x32_bf16 v[142:145], v[90:93], v[170:173], v[142:145]
	v_mfma_f32_16x16x32_bf16 v[138:141], v[98:101], v[170:173], v[138:141]
	v_mfma_f32_16x16x32_bf16 v[126:129], v[90:93], v[210:213], v[126:129]
	v_mfma_f32_16x16x32_bf16 v[122:125], v[98:101], v[210:213], v[122:125]
	v_mfma_f32_16x16x32_bf16 v[86:89], v[90:93], v[218:221], v[86:89]
	v_mfma_f32_16x16x32_bf16 v[82:85], v[98:101], v[218:221], v[82:85]
	v_mfma_f32_16x16x32_bf16 v[154:157], v[94:97], v[166:169], v[154:157]
	v_mfma_f32_16x16x32_bf16 v[158:161], v[102:105], v[166:169], v[158:161]
	v_mfma_f32_16x16x32_bf16 v[142:145], v[94:97], v[174:177], v[142:145]
	v_mfma_f32_16x16x32_bf16 v[138:141], v[102:105], v[174:177], v[138:141]
	v_mfma_f32_16x16x32_bf16 v[126:129], v[94:97], v[214:217], v[126:129]
	v_mfma_f32_16x16x32_bf16 v[122:125], v[102:105], v[214:217], v[122:125]
	v_mfma_f32_16x16x32_bf16 v[86:89], v[94:97], v[222:225], v[86:89]
	v_mfma_f32_16x16x32_bf16 v[82:85], v[102:105], v[222:225], v[82:85]
	s_setprio 0
	s_barrier
; #define PG8_STAGE(bufoff, gbase, voff) do { _Pragma("unroll") for (int _i = 0; _i < 2; ++_i) \
;         __builtin_amdgcn_global_load_lds((const unsigned*)((const char*)(gbase) + (voff)[_i]), (LAS unsigned*)(lds + (bufoff) + ldsw + _i * 8192), 16, 0, 0); } while (0)
; #define PG8_LDA(dst, b, h) do { _Pragma("unroll") for (int m = 0; m < 4; ++m) _Pragma("unroll") for (int k = 0; k < 2; ++k) dst[m][k] = *(const LAS bf16x8*)(lds + PG8_SA(b, h) + aoff + m * 2048 + k * 1024); } while (0)
; #define PG8_MMA(ai, bj, At, Bt) do { __builtin_amdgcn_s_setprio(1); _Pragma("unroll") for (int m = 0; m < 4; ++m) _Pragma("unroll") for (int n = 0; n < 2; ++n) _Pragma("unroll") for (int k = 0; k < 2; ++k) \
;         acc[ai][bj][m][n] = __builtin_amdgcn_mfma_f32_16x16x32_bf16(Bt[n][k], At[m][k], acc[ai][bj][m][n], 0, 0, 0); __builtin_amdgcn_s_setprio(0); } while (0)
; #define PG8_WAIT_V(n) asm volatile("s_waitcnt vmcnt(" #n ")" ::: "memory")
; #define PG8_WAIT_L(n) asm volatile("s_waitcnt lgkmcnt(" #n ")" ::: "memory")
; #define PG8_BAR __builtin_amdgcn_s_barrier()
; #define PG8_SCHED __builtin_amdgcn_sched_barrier(0)
; template <class Epi>
; __device__ __forceinline__ void gemm_phase(LAS unsigned char* lds, const Gemm g, const Order& S, const Epi& E) {
;     ...
;             PG8_LDA(At, 1, 1); PG8_STAGE(PG8_SB(1, 0), b3, voffB); PG8_STAGE(PG8_SB(1, 1), b3 + hstepB, voffB); PG8_STAGE(PG8_SA(1, 0), a3, voffA);
;             PG8_WAIT_V(8); PG8_WAIT_L(0); PG8_BAR; PG8_MMA(1, 0, At, B0); PG8_MMA(1, 1, At, B1); PG8_BAR; PG8_SCHED;
;         }
;         if (wr == 0) PG8_BAR;
	s_add_i32 s15, s15, s2
	v_lshl_add_u64 v[192:193], v[192:193], 0, s[86:87]
	s_mov_b32 m0, s15
	ds_read_b128 v[162:165], v208 offset:49152
	ds_read_b128 v[166:169], v208 offset:50176
	ds_read_b128 v[170:173], v208 offset:51200
	ds_read_b128 v[174:177], v208 offset:52224
	ds_read_b128 v[210:213], v208 offset:53248
	ds_read_b128 v[214:217], v208 offset:54272
	ds_read_b128 v[218:221], v208 offset:55296
	ds_read_b128 v[222:225], v208 offset:56320
	global_load_lds_dwordx4 v[192:193], off
	s_add_i32 m0, s15, 0x2000
	s_add_u32 s16, vcc_lo, 0x40080
	v_lshl_add_u64 v[192:193], v[200:201], 0, s[86:87]
	s_addc_u32 s17, vcc_hi, 0
	s_add_i32 s15, s18, s2
	global_load_lds_dwordx4 v[192:193], off
	v_lshl_add_u64 v[192:193], s[16:17], 0, v[194:195]
	s_mov_b32 m0, s15
	s_nop 0
	global_load_lds_dwordx4 v[192:193], off
	v_lshl_add_u64 v[192:193], s[16:17], 0, v[178:179]
	s_add_i32 m0, s15, 0x2000
	s_nop 0
	global_load_lds_dwordx4 v[192:193], off
	v_lshl_add_u64 v[192:193], v[226:227], 0, s[86:87]
	s_mov_b32 m0, s4
	s_nop 0
	global_load_lds_dwordx4 v[192:193], off
	v_lshl_add_u64 v[192:193], v[228:229], 0, s[86:87]
	s_mov_b32 m0, s5
	s_nop 0
	global_load_lds_dwordx4 v[192:193], off
	s_waitcnt vmcnt(8)
	s_waitcnt lgkmcnt(0)
	s_barrier
	s_setprio 1
	s_waitcnt lgkmcnt(0)
	v_mfma_f32_16x16x32_bf16 v[54:57], v[66:69], v[162:165], v[54:57]
	v_mfma_f32_16x16x32_bf16 v[50:53], v[74:77], v[162:165], v[50:53]
	v_mfma_f32_16x16x32_bf16 v[38:41], v[66:69], v[170:173], v[38:41]
	v_mfma_f32_16x16x32_bf16 v[34:37], v[74:77], v[170:173], v[34:37]
	v_mfma_f32_16x16x32_bf16 v[22:25], v[66:69], v[210:213], v[22:25]
	v_mfma_f32_16x16x32_bf16 v[18:21], v[74:77], v[210:213], v[18:21]
	v_mfma_f32_16x16x32_bf16 v[14:17], v[66:69], v[218:221], v[14:17]
	v_mfma_f32_16x16x32_bf16 v[10:13], v[74:77], v[218:221], v[10:13]
	v_mfma_f32_16x16x32_bf16 v[54:57], v[70:73], v[166:169], v[54:57]
	v_mfma_f32_16x16x32_bf16 v[50:53], v[78:81], v[166:169], v[50:53]
	v_mfma_f32_16x16x32_bf16 v[38:41], v[70:73], v[174:177], v[38:41]
	v_mfma_f32_16x16x32_bf16 v[34:37], v[78:81], v[174:177], v[34:37]
	v_mfma_f32_16x16x32_bf16 v[22:25], v[70:73], v[214:217], v[22:25]
	v_mfma_f32_16x16x32_bf16 v[18:21], v[78:81], v[214:217], v[18:21]
	v_mfma_f32_16x16x32_bf16 v[14:17], v[70:73], v[222:225], v[14:17]
	v_mfma_f32_16x16x32_bf16 v[10:13], v[78:81], v[222:225], v[10:13]
	s_setprio 0
	s_setprio 1
	v_mfma_f32_16x16x32_bf16 v[58:61], v[90:93], v[162:165], v[58:61]
	v_mfma_f32_16x16x32_bf16 v[62:65], v[98:101], v[162:165], v[62:65]
	v_mfma_f32_16x16x32_bf16 v[46:49], v[90:93], v[170:173], v[46:49]
	v_mfma_f32_16x16x32_bf16 v[42:45], v[98:101], v[170:173], v[42:45]
	v_mfma_f32_16x16x32_bf16 v[30:33], v[90:93], v[210:213], v[30:33]
	v_mfma_f32_16x16x32_bf16 v[26:29], v[98:101], v[210:213], v[26:29]
	v_mfma_f32_16x16x32_bf16 v[6:9], v[90:93], v[218:221], v[6:9]
	v_mfma_f32_16x16x32_bf16 v[2:5], v[98:101], v[218:221], v[2:5]
	v_mfma_f32_16x16x32_bf16 v[58:61], v[94:97], v[166:169], v[58:61]
	v_mfma_f32_16x16x32_bf16 v[62:65], v[102:105], v[166:169], v[62:65]
	v_mfma_f32_16x16x32_bf16 v[46:49], v[94:97], v[174:177], v[46:49]
	v_mfma_f32_16x16x32_bf16 v[42:45], v[102:105], v[174:177], v[42:45]
	v_mfma_f32_16x16x32_bf16 v[30:33], v[94:97], v[214:217], v[30:33]
	v_mfma_f32_16x16x32_bf16 v[26:29], v[102:105], v[214:217], v[26:29]
	v_mfma_f32_16x16x32_bf16 v[6:9], v[94:97], v[222:225], v[6:9]
	v_mfma_f32_16x16x32_bf16 v[2:5], v[102:105], v[222:225], v[2:5]
	s_setprio 0
	s_barrier
	s_add_i32 s14, s14, 2
	s_add_u32 s46, s46, 0x100
	s_addc_u32 s47, s47, 0
	s_add_u32 s12, s12, 0x100
	s_addc_u32 s13, s13, 0
	s_cmp_gt_u32 s14, 13
	s_cbranch_scc0 .LBB0_71
	s_and_b64 vcc, exec, s[56:57]
	s_cbranch_vccz .LBB0_74
	s_barrier

; template <class Epi>
; __device__ __forceinline__ void gemm_phase(LAS unsigned char* lds, const Gemm g, const Order& S, const Epi& E) {
;     ...
;     for (;;) {
;         const bool has_next = S.next(ui + 1, nxt);
;         const char* nA = has_next ? (const char*)(g.A + (size_t)nxt.g * g.gA) + (size_t)nxt.pm * tstepA : cA; const char* nB = has_next ? (const char*)(g.Bt + (size_t)nxt.g * g.gB) + (size_t)nxt.pn * tstepB : cB;
.LBB0_550:
	s_andn2_b64 vcc, exec, s[36:37]
	s_mov_b32 s13, s44
	s_mov_b32 s14, s46
	s_mov_b64 s[50:51], s[48:49]
	s_mov_b64 s[38:39], s[30:31]
	s_cbranch_vccz .LBB0_600
	s_mov_b32 s100, 1

; #define PG8_STAGE(bufoff, gbase, voff) do { _Pragma("unroll") for (int _i = 0; _i < 2; ++_i) \
;         __builtin_amdgcn_global_load_lds((const unsigned*)((const char*)(gbase) + (voff)[_i]), (LAS unsigned*)(lds + (bufoff) + ldsw + _i * 8192), 16, 0, 0); } while (0)
; #define PG8_LDA(dst, b, h) do { _Pragma("unroll") for (int m = 0; m < 4; ++m) _Pragma("unroll") for (int k = 0; k < 2; ++k) dst[m][k] = *(const LAS bf16x8*)(lds + PG8_SA(b, h) + aoff + m * 2048 + k * 1024); } while (0)
; #define PG8_LDB(dst, b, h) do { _Pragma("unroll") for (int n = 0; n < 2; ++n) _Pragma("unroll") for (int k = 0; k < 2; ++k) dst[n][k] = *(const LAS bf16x8*)(lds + PG8_SB(b, h) + boff + n * 2048 + k * 1024); } while (0)
; #define PG8_MMA(ai, bj, At, Bt) do { __builtin_amdgcn_s_setprio(1); _Pragma("unroll") for (int m = 0; m < 4; ++m) _Pragma("unroll") for (int n = 0; n < 2; ++n) _Pragma("unroll") for (int k = 0; k < 2; ++k) \
;         acc[ai][bj][m][n] = __builtin_amdgcn_mfma_f32_16x16x32_bf16(Bt[n][k], At[m][k], acc[ai][bj][m][n], 0, 0, 0); __builtin_amdgcn_s_setprio(0); } while (0)
; #define PG8_WAIT_V(n) asm volatile("s_waitcnt vmcnt(" #n ")" ::: "memory")
; #define PG8_WAIT_L(n) asm volatile("s_waitcnt lgkmcnt(" #n ")" ::: "memory")
; #define PG8_BAR __builtin_amdgcn_s_barrier()
; #define PG8_SCHED __builtin_amdgcn_sched_barrier(0)
; template <class Epi>
; __device__ __forceinline__ void gemm_phase(LAS unsigned char* lds, const Gemm g, const Order& S, const Epi& E) {
;     ...
;         for (int t = 0; t < nt; t += 2) {
;             const bool last = (t == nt - 2);
;             const char* a1 = cA + (size_t)(t + 1) * kstep;
;             const char* a2 = last ? nA : cA + (size_t)(t + 2) * kstep; const char* b2 = last ? nB : cB + (size_t)(t + 2) * kstep;
;             const char* a3 = a2 + kstep; const char* b3 = b2 + kstep;
;             PG8_LDB(B0, 0, 0); PG8_LDB(B1, 0, 1); PG8_SCHED; PG8_LDA(At, 0, 0); PG8_STAGE(PG8_SA(1, 1), a1 + hstepA, voffA);
;             PG8_WAIT_V(8); PG8_WAIT_L(0); PG8_BAR; PG8_MMA(0, 0, At, B0); PG8_MMA(0, 1, At, B1); PG8_BAR; PG8_SCHED;
.LBB0_554:
	s_add_u32 s47, s38, 0xfffc0080
	s_addc_u32 s50, s39, -1
	s_add_i32 s54, 0, 0x10000
	s_cmp_eq_u32 s45, 12
	s_cselect_b32 s53, s15, s50
	s_cselect_b32 s52, s16, s47
	s_cselect_b32 s51, s17, s20
	s_cselect_b32 s50, s18, s19
	s_add_i32 s47, 0, 0x14000
	v_add_u32_e32 v86, s54, v163
	v_add_u32_e32 v160, s47, v163
	ds_read_b128 v[66:69], v86
	ds_read_b128 v[74:77], v86 offset:1024
	ds_read_b128 v[82:85], v86 offset:2048
	ds_read_b128 v[86:89], v86 offset:3072
	ds_read_b128 v[156:159], v160
	ds_read_b128 v[166:169], v160 offset:1024
	ds_read_b128 v[170:173], v160 offset:2048
	ds_read_b128 v[174:177], v160 offset:3072
	v_lshl_add_u64 v[160:161], s[38:39], 0, v[152:153]
	s_add_i32 m0, s6, 0xc000
	ds_read_b128 v[178:181], v165
	ds_read_b128 v[182:185], v165 offset:1024
	ds_read_b128 v[186:189], v165 offset:2048
	ds_read_b128 v[190:193], v165 offset:3072
	ds_read_b128 v[204:207], v165 offset:4096
	ds_read_b128 v[208:211], v165 offset:5120
	ds_read_b128 v[212:215], v165 offset:6144
	ds_read_b128 v[216:219], v165 offset:7168
	global_load_lds_dwordx4 v[160:161], off
	v_lshl_add_u64 v[160:161], s[38:39], 0, v[154:155]
	s_add_i32 m0, s6, 0xe000
	s_nop 0
	global_load_lds_dwordx4 v[160:161], off
	s_cmp_lg_u32 s100, 0
	s_cbranch_scc1 .Lxr1_LBB0554
	s_waitcnt vmcnt(8)
	s_branch .Lxb1_LBB0554

; #define PG8_STAGE(bufoff, gbase, voff) do { _Pragma("unroll") for (int _i = 0; _i < 2; ++_i) \
;         __builtin_amdgcn_global_load_lds((const unsigned*)((const char*)(gbase) + (voff)[_i]), (LAS unsigned*)(lds + (bufoff) + ldsw + _i * 8192), 16, 0, 0); } while (0)
; #define PG8_LDA(dst, b, h) do { _Pragma("unroll") for (int m = 0; m < 4; ++m) _Pragma("unroll") for (int k = 0; k < 2; ++k) dst[m][k] = *(const LAS bf16x8*)(lds + PG8_SA(b, h) + aoff + m * 2048 + k * 1024); } while (0)
; #define PG8_MMA(ai, bj, At, Bt) do { __builtin_amdgcn_s_setprio(1); _Pragma("unroll") for (int m = 0; m < 4; ++m) _Pragma("unroll") for (int n = 0; n < 2; ++n) _Pragma("unroll") for (int k = 0; k < 2; ++k) \
;         acc[ai][bj][m][n] = __builtin_amdgcn_mfma_f32_16x16x32_bf16(Bt[n][k], At[m][k], acc[ai][bj][m][n], 0, 0, 0); __builtin_amdgcn_s_setprio(0); } while (0)
; #define PG8_WAIT_V(n) asm volatile("s_waitcnt vmcnt(" #n ")" ::: "memory")
; #define PG8_WAIT_L(n) asm volatile("s_waitcnt lgkmcnt(" #n ")" ::: "memory")
; #define PG8_BAR __builtin_amdgcn_s_barrier()
; #define PG8_SCHED __builtin_amdgcn_sched_barrier(0)
; template <class Epi>
; __device__ __forceinline__ void gemm_phase(LAS unsigned char* lds, const Gemm g, const Order& S, const Epi& E) {
;     ...
;             PG8_WAIT_V(8); PG8_WAIT_L(0); PG8_BAR; PG8_MMA(0, 0, At, B0); PG8_MMA(0, 1, At, B1); PG8_BAR; PG8_SCHED;
;             PG8_LDA(At, 0, 1); PG8_STAGE(PG8_SB(0, 0), b2, voffB); PG8_STAGE(PG8_SB(0, 1), b2 + hstepB, voffB); PG8_STAGE(PG8_SA(0, 0), a2, voffA);
;             PG8_WAIT_V(8); PG8_WAIT_L(0); PG8_BAR; PG8_MMA(1, 0, At, B0); PG8_MMA(1, 1, At, B1); PG8_BAR; PG8_SCHED;
.Lxb1_LBB0554:
	s_waitcnt lgkmcnt(0)
	s_barrier
	s_setprio 1
	s_waitcnt lgkmcnt(0)
	v_mfma_f32_16x16x32_bf16 v[142:145], v[66:69], v[178:181], v[142:145]
	v_mfma_f32_16x16x32_bf16 v[138:141], v[82:85], v[178:181], v[138:141]
	v_mfma_f32_16x16x32_bf16 v[126:129], v[66:69], v[186:189], v[126:129]
	v_mfma_f32_16x16x32_bf16 v[122:125], v[82:85], v[186:189], v[122:125]
	v_mfma_f32_16x16x32_bf16 v[110:113], v[66:69], v[204:207], v[110:113]
	v_mfma_f32_16x16x32_bf16 v[106:109], v[82:85], v[204:207], v[106:109]
	v_mfma_f32_16x16x32_bf16 v[94:97], v[66:69], v[212:215], v[94:97]
	v_mfma_f32_16x16x32_bf16 v[90:93], v[82:85], v[212:215], v[90:93]
	v_mfma_f32_16x16x32_bf16 v[142:145], v[74:77], v[182:185], v[142:145]
	v_mfma_f32_16x16x32_bf16 v[138:141], v[86:89], v[182:185], v[138:141]
	v_mfma_f32_16x16x32_bf16 v[126:129], v[74:77], v[190:193], v[126:129]
	v_mfma_f32_16x16x32_bf16 v[122:125], v[86:89], v[190:193], v[122:125]
	v_mfma_f32_16x16x32_bf16 v[110:113], v[74:77], v[208:211], v[110:113]
	v_mfma_f32_16x16x32_bf16 v[106:109], v[86:89], v[208:211], v[106:109]
	v_mfma_f32_16x16x32_bf16 v[94:97], v[74:77], v[216:219], v[94:97]
	v_mfma_f32_16x16x32_bf16 v[90:93], v[86:89], v[216:219], v[90:93]
	s_setprio 0
	s_setprio 1
	v_mfma_f32_16x16x32_bf16 v[134:137], v[156:159], v[178:181], v[134:137]
	v_mfma_f32_16x16x32_bf16 v[130:133], v[170:173], v[178:181], v[130:133]
	v_mfma_f32_16x16x32_bf16 v[118:121], v[156:159], v[186:189], v[118:121]
	v_mfma_f32_16x16x32_bf16 v[114:117], v[170:173], v[186:189], v[114:117]
	v_mfma_f32_16x16x32_bf16 v[102:105], v[156:159], v[204:207], v[102:105]
	v_mfma_f32_16x16x32_bf16 v[98:101], v[170:173], v[204:207], v[98:101]
	v_mfma_f32_16x16x32_bf16 v[78:81], v[156:159], v[212:215], v[78:81]
	v_mfma_f32_16x16x32_bf16 v[70:73], v[170:173], v[212:215], v[70:73]
	v_mfma_f32_16x16x32_bf16 v[134:137], v[166:169], v[182:185], v[134:137]
	v_mfma_f32_16x16x32_bf16 v[130:133], v[174:177], v[182:185], v[130:133]
	v_mfma_f32_16x16x32_bf16 v[118:121], v[166:169], v[190:193], v[118:121]
	v_mfma_f32_16x16x32_bf16 v[114:117], v[174:177], v[190:193], v[114:117]
	v_mfma_f32_16x16x32_bf16 v[102:105], v[166:169], v[208:211], v[102:105]
	v_mfma_f32_16x16x32_bf16 v[98:101], v[174:177], v[208:211], v[98:101]
	v_mfma_f32_16x16x32_bf16 v[78:81], v[166:169], v[216:219], v[78:81]
	v_mfma_f32_16x16x32_bf16 v[70:73], v[174:177], v[216:219], v[70:73]
	s_setprio 0
	s_barrier
	s_add_i32 s54, s54, s5
	v_lshl_add_u64 v[160:161], s[50:51], 0, v[150:151]
	s_mov_b32 m0, s54
	ds_read_b128 v[178:181], v165 offset:16384
	ds_read_b128 v[182:185], v165 offset:17408
	ds_read_b128 v[186:189], v165 offset:18432
	ds_read_b128 v[190:193], v165 offset:19456
	ds_read_b128 v[204:207], v165 offset:20480
	ds_read_b128 v[208:211], v165 offset:21504
	ds_read_b128 v[212:215], v165 offset:22528
	ds_read_b128 v[216:219], v165 offset:23552
	global_load_lds_dwordx4 v[160:161], off
	s_add_i32 m0, s54, 0x2000
	s_add_u32 s54, s50, 0x40000
	v_lshl_add_u64 v[220:221], s[50:51], 0, v[146:147]
	s_addc_u32 s55, s51, 0
	s_add_i32 s47, s47, s5
	global_load_lds_dwordx4 v[220:221], off
	v_lshl_add_u64 v[222:223], s[54:55], 0, v[150:151]
	s_mov_b32 m0, s47
	v_lshl_add_u64 v[224:225], s[52:53], 0, v[148:149]
	global_load_lds_dwordx4 v[222:223], off
	v_lshl_add_u64 v[222:223], s[54:55], 0, v[146:147]
	s_add_i32 m0, s47, 0x2000
	s_nop 0
	global_load_lds_dwordx4 v[222:223], off
	v_lshl_add_u64 v[222:223], s[52:53], 0, v[194:195]
	s_mov_b32 m0, s6
	s_nop 0
	global_load_lds_dwordx4 v[222:223], off
	s_mov_b32 m0, s7
	s_nop 0
	global_load_lds_dwordx4 v[224:225], off
	s_cmp_lg_u32 s100, 0
	s_cbranch_scc1 .Lxr2_LBB0554
	s_waitcnt vmcnt(8)
	s_branch .Lxb2_LBB0554

; #define PG8_STAGE(bufoff, gbase, voff) do { _Pragma("unroll") for (int _i = 0; _i < 2; ++_i) \
;         __builtin_amdgcn_global_load_lds((const unsigned*)((const char*)(gbase) + (voff)[_i]), (LAS unsigned*)(lds + (bufoff) + ldsw + _i * 8192), 16, 0, 0); } while (0)
; #define PG8_LDA(dst, b, h) do { _Pragma("unroll") for (int m = 0; m < 4; ++m) _Pragma("unroll") for (int k = 0; k < 2; ++k) dst[m][k] = *(const LAS bf16x8*)(lds + PG8_SA(b, h) + aoff + m * 2048 + k * 1024); } while (0)
; #define PG8_LDB(dst, b, h) do { _Pragma("unroll") for (int n = 0; n < 2; ++n) _Pragma("unroll") for (int k = 0; k < 2; ++k) dst[n][k] = *(const LAS bf16x8*)(lds + PG8_SB(b, h) + boff + n * 2048 + k * 1024); } while (0)
; #define PG8_MMA(ai, bj, At, Bt) do { __builtin_amdgcn_s_setprio(1); _Pragma("unroll") for (int m = 0; m < 4; ++m) _Pragma("unroll") for (int n = 0; n < 2; ++n) _Pragma("unroll") for (int k = 0; k < 2; ++k) \
;         acc[ai][bj][m][n] = __builtin_amdgcn_mfma_f32_16x16x32_bf16(Bt[n][k], At[m][k], acc[ai][bj][m][n], 0, 0, 0); __builtin_amdgcn_s_setprio(0); } while (0)
; #define PG8_WAIT_V(n) asm volatile("s_waitcnt vmcnt(" #n ")" ::: "memory")
; #define PG8_WAIT_L(n) asm volatile("s_waitcnt lgkmcnt(" #n ")" ::: "memory")
; #define PG8_BAR __builtin_amdgcn_s_barrier()
; #define PG8_SCHED __builtin_amdgcn_sched_barrier(0)
; template <class Epi>
; __device__ __forceinline__ void gemm_phase(LAS unsigned char* lds, const Gemm g, const Order& S, const Epi& E) {
;     ...
;             PG8_WAIT_V(8); PG8_WAIT_L(0); PG8_BAR; PG8_MMA(1, 0, At, B0); PG8_MMA(1, 1, At, B1); PG8_BAR; PG8_SCHED;
;             PG8_LDB(B0, 1, 0); PG8_LDB(B1, 1, 1); PG8_SCHED; PG8_LDA(At, 1, 0); PG8_STAGE(PG8_SA(0, 1), a2 + hstepA, voffA);
;             PG8_WAIT_V(8); PG8_WAIT_L(0); PG8_BAR; PG8_MMA(0, 0, At, B0); PG8_MMA(0, 1, At, B1); PG8_BAR; PG8_SCHED;
;             PG8_LDA(At, 1, 1); PG8_STAGE(PG8_SB(1, 0), b3, voffB); PG8_STAGE(PG8_SB(1, 1), b3 + hstepB, voffB); PG8_STAGE(PG8_SA(1, 0), a3, voffA);
;             PG8_WAIT_V(8); PG8_WAIT_L(0); PG8_BAR; PG8_MMA(1, 0, At, B0); PG8_MMA(1, 1, At, B1); PG8_BAR; PG8_SCHED;
.Lxb2_LBB0554:
	s_waitcnt lgkmcnt(0)
	s_barrier
	s_setprio 1
	s_waitcnt lgkmcnt(0)
	v_mfma_f32_16x16x32_bf16 v[62:65], v[66:69], v[178:181], v[62:65]
	v_mfma_f32_16x16x32_bf16 v[58:61], v[82:85], v[178:181], v[58:61]
	v_mfma_f32_16x16x32_bf16 v[46:49], v[66:69], v[186:189], v[46:49]
	v_mfma_f32_16x16x32_bf16 v[42:45], v[82:85], v[186:189], v[42:45]
	v_mfma_f32_16x16x32_bf16 v[30:33], v[66:69], v[204:207], v[30:33]
	v_mfma_f32_16x16x32_bf16 v[26:29], v[82:85], v[204:207], v[26:29]
	v_mfma_f32_16x16x32_bf16 v[14:17], v[66:69], v[212:215], v[14:17]
	v_mfma_f32_16x16x32_bf16 v[10:13], v[82:85], v[212:215], v[10:13]
	v_mfma_f32_16x16x32_bf16 v[62:65], v[74:77], v[182:185], v[62:65]
	v_mfma_f32_16x16x32_bf16 v[58:61], v[86:89], v[182:185], v[58:61]
	v_mfma_f32_16x16x32_bf16 v[46:49], v[74:77], v[190:193], v[46:49]
	v_mfma_f32_16x16x32_bf16 v[42:45], v[86:89], v[190:193], v[42:45]
	v_mfma_f32_16x16x32_bf16 v[30:33], v[74:77], v[208:211], v[30:33]
	v_mfma_f32_16x16x32_bf16 v[26:29], v[86:89], v[208:211], v[26:29]
	v_mfma_f32_16x16x32_bf16 v[14:17], v[74:77], v[216:219], v[14:17]
	v_mfma_f32_16x16x32_bf16 v[10:13], v[86:89], v[216:219], v[10:13]
	s_setprio 0
	s_setprio 1
	v_mfma_f32_16x16x32_bf16 v[54:57], v[156:159], v[178:181], v[54:57]
	v_mfma_f32_16x16x32_bf16 v[50:53], v[170:173], v[178:181], v[50:53]
	v_mfma_f32_16x16x32_bf16 v[38:41], v[156:159], v[186:189], v[38:41]
	v_mfma_f32_16x16x32_bf16 v[34:37], v[170:173], v[186:189], v[34:37]
	v_mfma_f32_16x16x32_bf16 v[22:25], v[156:159], v[204:207], v[22:25]
	v_mfma_f32_16x16x32_bf16 v[18:21], v[170:173], v[204:207], v[18:21]
	v_mfma_f32_16x16x32_bf16 v[6:9], v[156:159], v[212:215], v[6:9]
	v_mfma_f32_16x16x32_bf16 v[2:5], v[170:173], v[212:215], v[2:5]
	v_mfma_f32_16x16x32_bf16 v[54:57], v[166:169], v[182:185], v[54:57]
	v_mfma_f32_16x16x32_bf16 v[50:53], v[174:177], v[182:185], v[50:53]
	v_mfma_f32_16x16x32_bf16 v[38:41], v[166:169], v[190:193], v[38:41]
	v_mfma_f32_16x16x32_bf16 v[34:37], v[174:177], v[190:193], v[34:37]
	v_mfma_f32_16x16x32_bf16 v[22:25], v[166:169], v[208:211], v[22:25]
	v_mfma_f32_16x16x32_bf16 v[18:21], v[174:177], v[208:211], v[18:21]
	v_mfma_f32_16x16x32_bf16 v[6:9], v[166:169], v[216:219], v[6:9]
	v_mfma_f32_16x16x32_bf16 v[2:5], v[174:177], v[216:219], v[2:5]
	s_setprio 0
	s_barrier
	s_add_i32 s47, 0, 0x18000
	s_add_i32 s54, 0, 0x1c000
	v_add_u32_e32 v86, s47, v163
	v_add_u32_e32 v174, s54, v163
	ds_read_b128 v[66:69], v86
	ds_read_b128 v[74:77], v86 offset:1024
	ds_read_b128 v[82:85], v86 offset:2048
	ds_read_b128 v[86:89], v86 offset:3072
	ds_read_b128 v[156:159], v174
	ds_read_b128 v[166:169], v174 offset:1024
	ds_read_b128 v[170:173], v174 offset:2048
	ds_read_b128 v[174:177], v174 offset:3072
	s_add_u32 s52, s52, 0x40000
	s_addc_u32 s53, s53, 0
	s_mov_b32 m0, s8
	v_lshl_add_u64 v[226:227], s[52:53], 0, v[194:195]
	ds_read_b128 v[178:181], v165 offset:32768
	ds_read_b128 v[182:185], v165 offset:33792
	ds_read_b128 v[186:189], v165 offset:34816
	ds_read_b128 v[190:193], v165 offset:35840
	ds_read_b128 v[204:207], v165 offset:36864
	ds_read_b128 v[208:211], v165 offset:37888
	ds_read_b128 v[212:215], v165 offset:38912
	ds_read_b128 v[216:219], v165 offset:39936
	global_load_lds_dwordx4 v[226:227], off
	v_lshl_add_u64 v[226:227], s[52:53], 0, v[148:149]
	s_mov_b32 m0, s9
	s_nop 0
	global_load_lds_dwordx4 v[226:227], off
	s_waitcnt vmcnt(8)
	s_waitcnt lgkmcnt(0)
	s_barrier
	s_setprio 1
	s_waitcnt lgkmcnt(0)
	v_mfma_f32_16x16x32_bf16 v[142:145], v[66:69], v[178:181], v[142:145]
	v_mfma_f32_16x16x32_bf16 v[138:141], v[82:85], v[178:181], v[138:141]
	v_mfma_f32_16x16x32_bf16 v[126:129], v[66:69], v[186:189], v[126:129]
	v_mfma_f32_16x16x32_bf16 v[122:125], v[82:85], v[186:189], v[122:125]
	v_mfma_f32_16x16x32_bf16 v[110:113], v[66:69], v[204:207], v[110:113]
	v_mfma_f32_16x16x32_bf16 v[106:109], v[82:85], v[204:207], v[106:109]
	v_mfma_f32_16x16x32_bf16 v[94:97], v[66:69], v[212:215], v[94:97]
	v_mfma_f32_16x16x32_bf16 v[90:93], v[82:85], v[212:215], v[90:93]
	v_mfma_f32_16x16x32_bf16 v[142:145], v[74:77], v[182:185], v[142:145]
	v_mfma_f32_16x16x32_bf16 v[138:141], v[86:89], v[182:185], v[138:141]
	v_mfma_f32_16x16x32_bf16 v[126:129], v[74:77], v[190:193], v[126:129]
	v_mfma_f32_16x16x32_bf16 v[122:125], v[86:89], v[190:193], v[122:125]
	v_mfma_f32_16x16x32_bf16 v[110:113], v[74:77], v[208:211], v[110:113]
	v_mfma_f32_16x16x32_bf16 v[106:109], v[86:89], v[208:211], v[106:109]
	v_mfma_f32_16x16x32_bf16 v[94:97], v[74:77], v[216:219], v[94:97]
	v_mfma_f32_16x16x32_bf16 v[90:93], v[86:89], v[216:219], v[90:93]
	s_setprio 0
	s_setprio 1
	v_mfma_f32_16x16x32_bf16 v[134:137], v[156:159], v[178:181], v[134:137]
	v_mfma_f32_16x16x32_bf16 v[130:133], v[170:173], v[178:181], v[130:133]
	v_mfma_f32_16x16x32_bf16 v[118:121], v[156:159], v[186:189], v[118:121]
	v_mfma_f32_16x16x32_bf16 v[114:117], v[170:173], v[186:189], v[114:117]
	v_mfma_f32_16x16x32_bf16 v[102:105], v[156:159], v[204:207], v[102:105]
	v_mfma_f32_16x16x32_bf16 v[98:101], v[170:173], v[204:207], v[98:101]
	v_mfma_f32_16x16x32_bf16 v[78:81], v[156:159], v[212:215], v[78:81]
	v_mfma_f32_16x16x32_bf16 v[70:73], v[170:173], v[212:215], v[70:73]
	v_mfma_f32_16x16x32_bf16 v[134:137], v[166:169], v[182:185], v[134:137]
	v_mfma_f32_16x16x32_bf16 v[130:133], v[174:177], v[182:185], v[130:133]
	v_mfma_f32_16x16x32_bf16 v[118:121], v[166:169], v[190:193], v[118:121]
	v_mfma_f32_16x16x32_bf16 v[114:117], v[174:177], v[190:193], v[114:117]
	v_mfma_f32_16x16x32_bf16 v[102:105], v[166:169], v[208:211], v[102:105]
	v_mfma_f32_16x16x32_bf16 v[98:101], v[174:177], v[208:211], v[98:101]
	v_mfma_f32_16x16x32_bf16 v[78:81], v[166:169], v[216:219], v[78:81]
	v_mfma_f32_16x16x32_bf16 v[70:73], v[174:177], v[216:219], v[70:73]
	s_setprio 0
	s_barrier
; #define PG8_STAGE(bufoff, gbase, voff) do { _Pragma("unroll") for (int _i = 0; _i < 2; ++_i) \
;         __builtin_amdgcn_global_load_lds((const unsigned*)((const char*)(gbase) + (voff)[_i]), (LAS unsigned*)(lds + (bufoff) + ldsw + _i * 8192), 16, 0, 0); } while (0)
; #define PG8_LDA(dst, b, h) do { _Pragma("unroll") for (int m = 0; m < 4; ++m) _Pragma("unroll") for (int k = 0; k < 2; ++k) dst[m][k] = *(const LAS bf16x8*)(lds + PG8_SA(b, h) + aoff + m * 2048 + k * 1024); } while (0)
; #define PG8_MMA(ai, bj, At, Bt) do { __builtin_amdgcn_s_setprio(1); _Pragma("unroll") for (int m = 0; m < 4; ++m) _Pragma("unroll") for (int n = 0; n < 2; ++n) _Pragma("unroll") for (int k = 0; k < 2; ++k) \
;         acc[ai][bj][m][n] = __builtin_amdgcn_mfma_f32_16x16x32_bf16(Bt[n][k], At[m][k], acc[ai][bj][m][n], 0, 0, 0); __builtin_amdgcn_s_setprio(0); } while (0)
; #define PG8_WAIT_V(n) asm volatile("s_waitcnt vmcnt(" #n ")" ::: "memory")
; #define PG8_WAIT_L(n) asm volatile("s_waitcnt lgkmcnt(" #n ")" ::: "memory")
; #define PG8_BAR __builtin_amdgcn_s_barrier()
; #define PG8_SCHED __builtin_amdgcn_sched_barrier(0)
; template <class Epi>
; __device__ __forceinline__ void gemm_phase(LAS unsigned char* lds, const Gemm g, const Order& S, const Epi& E) {
;     ...
;             PG8_LDA(At, 1, 1); PG8_STAGE(PG8_SB(1, 0), b3, voffB); PG8_STAGE(PG8_SB(1, 1), b3 + hstepB, voffB); PG8_STAGE(PG8_SA(1, 0), a3, voffA);
;             PG8_WAIT_V(8); PG8_WAIT_L(0); PG8_BAR; PG8_MMA(1, 0, At, B0); PG8_MMA(1, 1, At, B1); PG8_BAR; PG8_SCHED;
;         }
;         if (wr == 0) PG8_BAR;
	s_add_i32 s47, s47, s5
	v_lshl_add_u64 v[160:161], v[160:161], 0, s[86:87]
	s_mov_b32 m0, s47
	ds_read_b128 v[178:181], v165 offset:49152
	ds_read_b128 v[182:185], v165 offset:50176
	ds_read_b128 v[186:189], v165 offset:51200
	ds_read_b128 v[190:193], v165 offset:52224
	ds_read_b128 v[204:207], v165 offset:53248
	ds_read_b128 v[208:211], v165 offset:54272
	ds_read_b128 v[212:215], v165 offset:55296
	ds_read_b128 v[216:219], v165 offset:56320
	global_load_lds_dwordx4 v[160:161], off
	s_add_i32 m0, s47, 0x2000
	s_add_u32 s50, s50, 0x40080
	v_lshl_add_u64 v[160:161], v[220:221], 0, s[86:87]
	s_addc_u32 s51, s51, 0
	s_add_i32 s47, s54, s5
	global_load_lds_dwordx4 v[160:161], off
	v_lshl_add_u64 v[160:161], s[50:51], 0, v[150:151]
	s_mov_b32 m0, s47
	s_nop 0
	global_load_lds_dwordx4 v[160:161], off
	v_lshl_add_u64 v[160:161], s[50:51], 0, v[146:147]
	s_add_i32 m0, s47, 0x2000
	s_nop 0
	global_load_lds_dwordx4 v[160:161], off
	v_lshl_add_u64 v[160:161], v[222:223], 0, s[86:87]
	s_mov_b32 m0, s10
	s_nop 0
	global_load_lds_dwordx4 v[160:161], off
	v_lshl_add_u64 v[160:161], v[224:225], 0, s[86:87]
	s_mov_b32 m0, s11
	s_nop 0
	global_load_lds_dwordx4 v[160:161], off
	s_waitcnt vmcnt(8)
	s_waitcnt lgkmcnt(0)
	s_barrier
	s_setprio 1
	s_waitcnt lgkmcnt(0)
	v_mfma_f32_16x16x32_bf16 v[62:65], v[66:69], v[178:181], v[62:65]
	v_mfma_f32_16x16x32_bf16 v[58:61], v[82:85], v[178:181], v[58:61]
	v_mfma_f32_16x16x32_bf16 v[46:49], v[66:69], v[186:189], v[46:49]
	v_mfma_f32_16x16x32_bf16 v[42:45], v[82:85], v[186:189], v[42:45]
	v_mfma_f32_16x16x32_bf16 v[30:33], v[66:69], v[204:207], v[30:33]
	v_mfma_f32_16x16x32_bf16 v[26:29], v[82:85], v[204:207], v[26:29]
	v_mfma_f32_16x16x32_bf16 v[14:17], v[66:69], v[212:215], v[14:17]
	v_mfma_f32_16x16x32_bf16 v[10:13], v[82:85], v[212:215], v[10:13]
	v_mfma_f32_16x16x32_bf16 v[62:65], v[74:77], v[182:185], v[62:65]
	v_mfma_f32_16x16x32_bf16 v[58:61], v[86:89], v[182:185], v[58:61]
	v_mfma_f32_16x16x32_bf16 v[46:49], v[74:77], v[190:193], v[46:49]
	v_mfma_f32_16x16x32_bf16 v[42:45], v[86:89], v[190:193], v[42:45]
	v_mfma_f32_16x16x32_bf16 v[30:33], v[74:77], v[208:211], v[30:33]
	v_mfma_f32_16x16x32_bf16 v[26:29], v[86:89], v[208:211], v[26:29]
	v_mfma_f32_16x16x32_bf16 v[14:17], v[74:77], v[216:219], v[14:17]
	v_mfma_f32_16x16x32_bf16 v[10:13], v[86:89], v[216:219], v[10:13]
	s_setprio 0
	s_setprio 1
	v_mfma_f32_16x16x32_bf16 v[54:57], v[156:159], v[178:181], v[54:57]
	v_mfma_f32_16x16x32_bf16 v[50:53], v[170:173], v[178:181], v[50:53]
	v_mfma_f32_16x16x32_bf16 v[38:41], v[156:159], v[186:189], v[38:41]
	v_mfma_f32_16x16x32_bf16 v[34:37], v[170:173], v[186:189], v[34:37]
	v_mfma_f32_16x16x32_bf16 v[22:25], v[156:159], v[204:207], v[22:25]
	v_mfma_f32_16x16x32_bf16 v[18:21], v[170:173], v[204:207], v[18:21]
	v_mfma_f32_16x16x32_bf16 v[6:9], v[156:159], v[212:215], v[6:9]
	v_mfma_f32_16x16x32_bf16 v[2:5], v[170:173], v[212:215], v[2:5]
	v_mfma_f32_16x16x32_bf16 v[54:57], v[166:169], v[182:185], v[54:57]
	v_mfma_f32_16x16x32_bf16 v[50:53], v[174:177], v[182:185], v[50:53]
	v_mfma_f32_16x16x32_bf16 v[38:41], v[166:169], v[190:193], v[38:41]
	v_mfma_f32_16x16x32_bf16 v[34:37], v[174:177], v[190:193], v[34:37]
	v_mfma_f32_16x16x32_bf16 v[22:25], v[166:169], v[208:211], v[22:25]
	v_mfma_f32_16x16x32_bf16 v[18:21], v[174:177], v[208:211], v[18:21]
	v_mfma_f32_16x16x32_bf16 v[6:9], v[166:169], v[216:219], v[6:9]
	v_mfma_f32_16x16x32_bf16 v[2:5], v[174:177], v[216:219], v[2:5]
	s_setprio 0
	s_barrier
	s_add_i32 s45, s45, 2
	s_add_u32 s38, s38, 0x100
	s_addc_u32 s39, s39, 0
	s_add_u32 s19, s19, 0x100
	s_addc_u32 s20, s20, 0
	s_cmp_gt_u32 s45, 13
	s_cbranch_scc0 .LBB0_554
	s_and_b64 vcc, exec, s[42:43]
	s_cbranch_vccz .LBB0_557
	s_barrier

; __global__ void __launch_bounds__(NTHR, 2) fwd_kernel(Params P) {
	.amdhsa_kernel _Z10fwd_kernel6Params
		.amdhsa_group_segment_fixed_size 0
		.amdhsa_private_segment_fixed_size 0
		.amdhsa_kernarg_size 440
		.amdhsa_user_sgpr_count 2
		.amdhsa_user_sgpr_dispatch_ptr 0
		.amdhsa_user_sgpr_queue_ptr 0
		.amdhsa_user_sgpr_kernarg_segment_ptr 1
		.amdhsa_user_sgpr_dispatch_id 0
		.amdhsa_user_sgpr_kernarg_preload_length 0
		.amdhsa_user_sgpr_kernarg_preload_offset 0
		.amdhsa_user_sgpr_private_segment_size 0
		.amdhsa_uses_dynamic_stack 0
		.amdhsa_enable_private_segment 0
		.amdhsa_system_sgpr_workgroup_id_x 1
		.amdhsa_system_sgpr_workgroup_id_y 0
		.amdhsa_system_sgpr_workgroup_id_z 0
		.amdhsa_system_sgpr_workgroup_info 0
		.amdhsa_system_vgpr_workitem_id 0
		.amdhsa_next_free_vgpr 256
		.amdhsa_next_free_sgpr 102
		.amdhsa_accum_offset 256
		.amdhsa_reserve_vcc 1
		.amdhsa_float_round_mode_32 0
		.amdhsa_float_round_mode_16_64 0
		.amdhsa_float_denorm_mode_32 3
		.amdhsa_float_denorm_mode_16_64 3
		.amdhsa_dx10_clamp 1
		.amdhsa_ieee_mode 1
		.amdhsa_fp16_overflow 0
		.amdhsa_tg_split 0
		.amdhsa_exception_fp_ieee_invalid_op 0
		.amdhsa_exception_fp_denorm_src 0
		.amdhsa_exception_fp_ieee_div_zero 0
		.amdhsa_exception_fp_ieee_overflow 0
		.amdhsa_exception_fp_ieee_underflow 0
		.amdhsa_exception_fp_ieee_inexact 0
		.amdhsa_exception_int_div_zero 0
	.end_amdhsa_kernel

; __global__ void __launch_bounds__(NTHR, 2) fwd_kernel(Params P) {
amdhsa.kernels:
  - .agpr_count:     0
    .args:
      - .offset:         0
        .size:           184
        .value_kind:     by_value
      - .offset:         184
        .size:           4
        .value_kind:     hidden_block_count_x
      - .offset:         188
        .size:           4
        .value_kind:     hidden_block_count_y
      - .offset:         192
        .size:           4
        .value_kind:     hidden_block_count_z
      - .offset:         196
        .size:           2
        .value_kind:     hidden_group_size_x
      - .offset:         198
        .size:           2
        .value_kind:     hidden_group_size_y
      - .offset:         200
        .size:           2
        .value_kind:     hidden_group_size_z
      - .offset:         202
        .size:           2
        .value_kind:     hidden_remainder_x
      - .offset:         204
        .size:           2
        .value_kind:     hidden_remainder_y
      - .offset:         206
        .size:           2
        .value_kind:     hidden_remainder_z
      - .offset:         224
        .size:           8
        .value_kind:     hidden_global_offset_x
      - .offset:         232
        .size:           8
        .value_kind:     hidden_global_offset_y
      - .offset:         240
        .size:           8
        .value_kind:     hidden_global_offset_z
      - .offset:         248
        .size:           2
        .value_kind:     hidden_grid_dims
      - .offset:         304
        .size:           4
        .value_kind:     hidden_dynamic_lds_size
    .group_segment_fixed_size: 0
    .kernarg_segment_align: 8
    .kernarg_segment_size: 440
    .language:       OpenCL C
    .language_version:
      - 2
      - 0
    .max_flat_workgroup_size: 512
    .name:           _Z10fwd_kernel6Params
    .private_segment_fixed_size: 0
    .sgpr_count:     108
    .sgpr_spill_count: 314
    .symbol:         _Z10fwd_kernel6Params.kd
    .uniform_work_group_size: 1
    .uses_dynamic_stack: false
    .vgpr_count:     256
    .vgpr_spill_count: 0
    .wavefront_size: 64
